# UP epilogue stores write-through sc1 (store latency hidden by counted waits; lighter L2 flush at the barrier)
# baseline (speedup 1.0000x reference)
; template <int EPI>
; __device__ __forceinline__ void epilogue(const Params& p, f32x4 (&acc)[2][2][4][2], const int pm, const int pn, const int wr, const int wc, const int fr, const int fq) {
;     ...
;     float* HA0 = (float*)(ws + OFF_HA0); float* HG0 = (float*)(ws + OFF_HG0); float* HA1 = (float*)(ws + OFF_HA1);
;     const bool prompt = (pm < MP / 256);
;     const int jb = pn * 128 + wc * 32 + fq * 8;
;     f32x4 w0[2], w1[2], w2[2], cb[2];
; #pragma unroll
;     for (int bj = 0; bj < 2; ++bj) {
;       w0[bj] = *(const f32x4*)(p.in[23] + jb + bj * 4); w1[bj] = *(const f32x4*)(p.in[23] + DFF + jb + bj * 4); w2[bj] = *(const f32x4*)(p.in[23] + 2 * DFF + jb + bj * 4);
;       cb[bj] = *(const f32x4*)(p.in[24] + jb + bj * 4);
;     }
; #pragma unroll
;     for (int ai = 0; ai < 2; ++ai) {
;       const int rblk = pm * 256 + ai * 128 + wr * 64;
; #pragma unroll
;       for (int m = 0; m < 4; ++m) {
;         const int row = rblk + m * 16 + fr;
;         u32x2 ho[2]; bool defer = false;
; #pragma unroll
;         for (int bj = 0; bj < 2; ++bj) {
;           const int j0 = jb + bj * 4;
;           const f32x4 a0 = acc[ai][bj][m][0], g = acc[ai][bj][m][1];
;           f32x4 am1, am2;
;           if (prompt) {
;             f32x4 o1 = f32x4{0.f, 0.f, 0.f, 0.f}, o2 = o1;
;             if (m > 0) { o1 = ror1v(acc[ai][bj][m > 0 ? m - 1 : 0][0]); o2 = ror2v(acc[ai][bj][m > 0 ? m - 1 : 0][0]); }
;             am1 = shr1v(o1, a0); am2 = shr2v(o2, a0);
;             if (m == 0 && fr < 2 && (row & 2047) >= 2) defer = true;
;             if (m == 3 && fr >= 14) *(f32x4*)(HA1 + ((size_t)(rblk >> 6) * 2 + (fr - 14)) * DFF + j0) = a0;
;             const int pos = row & 2047;
;             if (pos >= 2046) *(f32x4*)(p.out + O_CP + ((size_t)(row >> 11) * 2 + (pos - 2046)) * DFF + j0) = a0;
;           } else {
;             const int sidx = row - MP, b = sidx >> 2, tt = sidx & 3;
;             const f32x4 st0 = *(const f32x4*)(p.in[6] + ((size_t)b * 2 + 0) * DFF + j0);
;             const f32x4 st1 = *(const f32x4*)(p.in[6] + ((size_t)b * 2 + 1) * DFF + j0);
;             const f32x4 s1 = ror1v(a0), s2 = ror2v(a0);
;             am1 = (tt >= 1) ? s1 : st1;
;             am2 = (tt >= 2) ? s2 : ((tt == 1) ? st1 : st0);
;             if (tt >= 2) *(f32x4*)(p.out + O_CS + ((size_t)b * 2 + (tt - 2)) * DFF + j0) = a0;
;           }
.LBB0_973:
	v_lshl_or_b32 v214, s54, 7, v187
	v_ashrrev_i32_e32 v215, 31, v214
	v_readlane_b32 s80, v244, 35
	v_readlane_b32 s56, v244, 4
	v_lshlrev_b64 v[218:219], 2, v[214:215]
	v_readlane_b32 s94, v244, 49
	v_readlane_b32 s95, v244, 50
	v_readlane_b32 s57, v244, 5
	v_lshl_add_u64 v[46:47], s[36:37], 0, v[218:219]
	v_lshl_add_u64 v[42:43], s[94:95], 0, v[218:219]
	v_lshl_add_u64 v[50:51], s[38:39], 0, v[218:219]
	v_lshl_add_u64 v[70:71], s[56:57], 0, v[218:219]
	global_load_dwordx4 v[38:41], v[42:43], off offset:16
	global_load_dwordx4 v[54:57], v[42:43], off
	s_nop 0
	global_load_dwordx4 v[42:45], v[46:47], off offset:16
	global_load_dwordx4 v[58:61], v[46:47], off
	s_nop 0
	global_load_dwordx4 v[46:49], v[50:51], off offset:16
	global_load_dwordx4 v[66:69], v[50:51], off
	s_nop 0
	global_load_dwordx4 v[50:53], v[70:71], off offset:16
	s_nop 0
	global_load_dwordx4 v[70:73], v[70:71], off
	v_readlane_b32 s58, v244, 6
	v_readlane_b32 s59, v244, 7
	s_cmp_gt_i32 s18, 63
	s_cselect_b64 s[58:59], -1, 0
	s_lshl_b32 s47, s18, 8
	s_add_i32 s47, s47, s71
	v_or_b32_e32 v201, s47, v200
	v_add_u32_e32 v162, 0xffffc000, v201
	v_readlane_b32 s81, v244, 36
	v_readlane_b32 s82, v244, 37
	v_readlane_b32 s83, v244, 38
	v_readlane_b32 s84, v244, 39
	v_readlane_b32 s85, v244, 40
	v_readlane_b32 s86, v244, 41
	v_readlane_b32 s87, v244, 42
	v_readlane_b32 s88, v244, 43
	v_readlane_b32 s89, v244, 44
	v_readlane_b32 s90, v244, 45
	v_readlane_b32 s91, v244, 46
	v_readlane_b32 s92, v244, 47
	v_readlane_b32 s93, v244, 48
	v_ashrrev_i32_e32 v162, 2, v162
	v_ashrrev_i32_e32 v163, 31, v162
	v_readlane_b32 s80, v244, 14
	s_and_b32 s18, s47, 0x7c0
	v_mad_i64_i32 v[164:165], s[54:55], v162, s77, 0
	v_lshl_add_u64 v[162:163], v[162:163], 1, v[202:203]
	v_readlane_b32 s92, v244, 26
	v_readlane_b32 s93, v244, 27
	s_cmp_lg_u32 s18, 0
	v_mad_u64_u32 v[220:221], s[54:55], v162, s78, 0
	v_lshl_add_u64 v[180:181], s[92:93], 0, v[164:165]
	s_cselect_b64 s[18:19], -1, 0
	v_mad_i32_i24 v221, v163, s78, v221
	s_mov_b64 s[54:55], -1
	s_and_b64 vcc, exec, s[58:59]
	v_lshl_add_u64 v[178:179], v[214:215], 2, v[180:181]
	v_readlane_b32 s60, v244, 8
	v_readlane_b32 s61, v244, 9
	v_readlane_b32 s62, v244, 10
	v_readlane_b32 s63, v244, 11
	v_readlane_b32 s81, v244, 15
	v_readlane_b32 s82, v244, 16
	v_readlane_b32 s83, v244, 17
	v_readlane_b32 s84, v244, 18
	v_readlane_b32 s85, v244, 19
	v_readlane_b32 s86, v244, 20
	v_readlane_b32 s87, v244, 21
	v_readlane_b32 s88, v244, 22
	v_readlane_b32 s89, v244, 23
	v_readlane_b32 s90, v244, 24
	v_readlane_b32 s91, v244, 25
	v_readlane_b32 s94, v244, 28
	v_readlane_b32 s95, v244, 29
	s_cbranch_vccz .LBB0_977
	v_add_co_u32_e32 v166, vcc, 0x2000, v178
	v_mov_b32_e32 v174, 0
	s_nop 0
	v_addc_co_u32_e32 v167, vcc, 0, v179, vcc
	global_load_dwordx4 v[162:165], v[178:179], off
	s_nop 0
	global_load_dwordx4 v[166:169], v[166:167], off offset:3072
	v_mov_b32_e32 v175, 0
	v_mov_b32_e32 v176, 0
	v_mov_b32_e32 v177, 0
	v_mov_b32_e32 v170, 0
	v_mov_b32_e32 v171, 0
	v_mov_b32_e32 v172, 0
	v_mov_b32_e32 v173, 0
	v_mov_b32_dpp v174, v150 row_ror:1 row_mask:0xf bank_mask:0xf
	v_mov_b32_dpp v175, v151 row_ror:1 row_mask:0xf bank_mask:0xf
	v_mov_b32_dpp v176, v152 row_ror:1 row_mask:0xf bank_mask:0xf
	v_mov_b32_dpp v177, v153 row_ror:1 row_mask:0xf bank_mask:0xf
	v_mov_b32_dpp v170, v150 row_ror:2 row_mask:0xf bank_mask:0xf
	v_mov_b32_dpp v171, v151 row_ror:2 row_mask:0xf bank_mask:0xf
	v_mov_b32_dpp v172, v152 row_ror:2 row_mask:0xf bank_mask:0xf
	v_mov_b32_dpp v173, v153 row_ror:2 row_mask:0xf bank_mask:0xf
	s_waitcnt vmcnt(0)
	v_cndmask_b32_e64 v165, v165, v169, s[10:11]
	v_cndmask_b32_e64 v164, v164, v168, s[10:11]
	v_cndmask_b32_e64 v163, v163, v167, s[10:11]
	v_cndmask_b32_e64 v162, v162, v166, s[10:11]
	s_and_saveexec_b64 s[54:55], s[8:9]
	s_cbranch_execz .LBB0_976
	v_lshl_add_u64 v[162:163], s[42:43], 0, v[220:221]
	v_lshl_add_u64 v[162:163], v[214:215], 2, v[162:163]
	global_store_dwordx4 v[162:163], v[150:153], off sc1
	v_mov_b64_e32 v[162:163], v[170:171]
	v_mov_b64_e32 v[164:165], v[172:173]

; __device__ __forceinline__ float gelu_tanh(float x) { float z = 1.5957691216057308f * (x + 0.044715f * x * x * x); return x * rcp_nr(1.f + __expf(fminf(-z, 80.f))); }
; __device__ __forceinline__ u32x2 pk4(f32x4 v) { u32x2 r; r.x = pk2(v.x, v.y); r.y = pk2(v.z, v.w); return r; }
; __device__ __forceinline__ f32x4 ror1v(f32x4 v) { return f32x4{dpp_ror1(v.x), dpp_ror1(v.y), dpp_ror1(v.z), dpp_ror1(v.w)}; }
; __device__ __forceinline__ f32x4 ror2v(f32x4 v) { return f32x4{dpp_ror2(v.x), dpp_ror2(v.y), dpp_ror2(v.z), dpp_ror2(v.w)}; }
; template <int EPI>
; __device__ __forceinline__ void epilogue(const Params& p, f32x4 (&acc)[2][2][4][2], const int pm, const int pn, const int wr, const int wc, const int fr, const int fq) {
;     ...
;             if (m == 0 && fr < 2 && (row & 2047) >= 2) defer = true;
;             if (m == 3 && fr >= 14) *(f32x4*)(HA1 + ((size_t)(rblk >> 6) * 2 + (fr - 14)) * DFF + j0) = a0;
;             const int pos = row & 2047;
;             if (pos >= 2046) *(f32x4*)(p.out + O_CP + ((size_t)(row >> 11) * 2 + (pos - 2046)) * DFF + j0) = a0;
;           } else {
;             const int sidx = row - MP, b = sidx >> 2, tt = sidx & 3;
;             const f32x4 st0 = *(const f32x4*)(p.in[6] + ((size_t)b * 2 + 0) * DFF + j0);
;             const f32x4 st1 = *(const f32x4*)(p.in[6] + ((size_t)b * 2 + 1) * DFF + j0);
;             const f32x4 s1 = ror1v(a0), s2 = ror2v(a0);
;             am1 = (tt >= 1) ? s1 : st1;
;             am2 = (tt >= 2) ? s2 : ((tt == 1) ? st1 : st0);
;             if (tt >= 2) *(f32x4*)(p.out + O_CS + ((size_t)b * 2 + (tt - 2)) * DFF + j0) = a0;
;           }
;           f32x4 h;
;           h.x = gelu_tanh(cb[bj].x + w0[bj].x * am2.x + w1[bj].x * am1.x + w2[bj].x * a0.x) * g.x;
;           h.y = gelu_tanh(cb[bj].y + w0[bj].y * am2.y + w1[bj].y * am1.y + w2[bj].y * a0.y) * g.y;
;           h.z = gelu_tanh(cb[bj].z + w0[bj].z * am2.z + w1[bj].z * am1.z + w2[bj].z * a0.z) * g.z;
;           h.w = gelu_tanh(cb[bj].w + w0[bj].w * am2.w + w1[bj].w * am1.w + w2[bj].w * a0.w) * g.w;
;           ho[bj] = pk4(h);
;           if (defer) {
;             *(f32x4*)(HA0 + ((size_t)(rblk >> 6) * 2 + fr) * DFF + j0) = a0;
;             *(f32x4*)(HG0 + ((size_t)(rblk >> 6) * 2 + fr) * DFF + j0) = g;
.LBB0_979:
	s_ashr_i32 s18, s47, 6
	s_ashr_i32 s19, s18, 31
	s_lshl_b64 s[54:55], s[18:19], 1
	v_add_u32_e32 v174, s54, v200
	v_mov_b64_e32 v[170:171], s[30:31]
	v_mov_b64_e32 v[172:173], s[40:41]
	v_mad_i64_i32 v[170:171], s[18:19], v174, s78, v[170:171]
	v_mad_i64_i32 v[172:173], s[18:19], v174, s78, v[172:173]
	v_lshl_add_u64 v[222:223], v[170:171], 0, v[218:219]
	v_lshl_add_u64 v[224:225], v[172:173], 0, v[218:219]
	s_and_saveexec_b64 s[18:19], s[60:61]
	s_cbranch_execz .LBB0_981
	global_store_dwordx4 v[222:223], v[150:153], off sc1
	global_store_dwordx4 v[224:225], v[158:161], off sc1
.LBB0_981:
	s_or_b64 exec, exec, s[18:19]
	v_or_b32_e32 v216, 4, v214
	v_cndmask_b32_e64 v170, 0, 1, s[58:59]
	s_mov_b64 s[62:63], -1
	v_cmp_ne_u32_e64 s[18:19], 1, v170
	s_andn2_b64 vcc, exec, s[58:59]
	v_ashrrev_i32_e32 v217, 31, v216
	s_cbranch_vccnz .LBB0_985
	v_lshl_add_u64 v[170:171], v[216:217], 2, v[180:181]
	v_add_co_u32_e32 v174, vcc, 0x2000, v170
	v_mov_b32_e32 v198, 0
	s_nop 0
	v_addc_co_u32_e32 v175, vcc, 0, v171, vcc
	global_load_dwordx4 v[170:173], v[178:179], off offset:16
	s_nop 0
	global_load_dwordx4 v[174:177], v[174:175], off offset:3072
	v_mov_b32_e32 v226, 0
	v_mov_b32_e32 v227, 0
	v_mov_b32_e32 v228, 0
	v_mov_b32_e32 v178, 0
	v_mov_b32_e32 v179, 0
	v_mov_b32_e32 v180, 0
	v_mov_b32_e32 v181, 0
	v_mov_b32_dpp v198, v146 row_ror:1 row_mask:0xf bank_mask:0xf
	v_mov_b32_dpp v226, v147 row_ror:1 row_mask:0xf bank_mask:0xf
	v_mov_b32_dpp v227, v148 row_ror:1 row_mask:0xf bank_mask:0xf
	v_mov_b32_dpp v228, v149 row_ror:1 row_mask:0xf bank_mask:0xf
	v_mov_b32_dpp v178, v146 row_ror:2 row_mask:0xf bank_mask:0xf
	v_mov_b32_dpp v179, v147 row_ror:2 row_mask:0xf bank_mask:0xf
	v_mov_b32_dpp v180, v148 row_ror:2 row_mask:0xf bank_mask:0xf
	v_mov_b32_dpp v181, v149 row_ror:2 row_mask:0xf bank_mask:0xf
	s_waitcnt vmcnt(0)
	v_cndmask_b32_e64 v173, v173, v177, s[10:11]
	v_cndmask_b32_e64 v172, v172, v176, s[10:11]
	v_cndmask_b32_e64 v171, v171, v175, s[10:11]
	v_cndmask_b32_e64 v170, v170, v174, s[10:11]
	s_and_saveexec_b64 s[58:59], s[8:9]
	s_cbranch_execz .LBB0_984
	v_lshl_add_u64 v[170:171], s[42:43], 0, v[220:221]
	v_lshl_add_u64 v[170:171], v[214:215], 2, v[170:171]
	global_store_dwordx4 v[170:171], v[146:149], off offset:16 sc1
	v_mov_b64_e32 v[170:171], v[178:179]
	v_mov_b64_e32 v[172:173], v[180:181]

; __device__ __forceinline__ float gelu_tanh(float x) { float z = 1.5957691216057308f * (x + 0.044715f * x * x * x); return x * rcp_nr(1.f + __expf(fminf(-z, 80.f))); }
; __device__ __forceinline__ u32x2 pk4(f32x4 v) { u32x2 r; r.x = pk2(v.x, v.y); r.y = pk2(v.z, v.w); return r; }
; template <int EPI>
; __device__ __forceinline__ void epilogue(const Params& p, f32x4 (&acc)[2][2][4][2], const int pm, const int pn, const int wr, const int wc, const int fr, const int fq) {
;     ...
;           f32x4 h;
;           h.x = gelu_tanh(cb[bj].x + w0[bj].x * am2.x + w1[bj].x * am1.x + w2[bj].x * a0.x) * g.x;
;           h.y = gelu_tanh(cb[bj].y + w0[bj].y * am2.y + w1[bj].y * am1.y + w2[bj].y * a0.y) * g.y;
;           h.z = gelu_tanh(cb[bj].z + w0[bj].z * am2.z + w1[bj].z * am1.z + w2[bj].z * a0.z) * g.z;
;           h.w = gelu_tanh(cb[bj].w + w0[bj].w * am2.w + w1[bj].w * am1.w + w2[bj].w * a0.w) * g.w;
;           ho[bj] = pk4(h);
;           if (defer) {
;             *(f32x4*)(HA0 + ((size_t)(rblk >> 6) * 2 + fr) * DFF + j0) = a0;
;             *(f32x4*)(HG0 + ((size_t)(rblk >> 6) * 2 + fr) * DFF + j0) = g;
;           }
;         }
;         if (!defer) *(u32x4*)(H + (size_t)row * DFF + jb) = u32x4{ho[0].x, ho[0].y, ho[1].x, ho[1].y};
.LBB0_987:
	s_xor_b64 s[56:57], s[60:61], -1
	v_readlane_b32 s60, v244, 0
	v_readlane_b32 s62, v244, 2
	v_readlane_b32 s63, v244, 3
	v_readlane_b32 s61, v244, 1
	s_nop 0
	v_lshl_add_u64 v[178:179], v[214:215], 1, s[62:63]
	s_and_saveexec_b64 s[58:59], s[56:57]
	s_xor_b64 s[56:57], exec, s[58:59]
	s_cbranch_execz .LBB0_989
	s_waitcnt vmcnt(0)
	v_pk_fma_f32 v[162:163], v[54:55], v[162:163], v[70:71]
	v_pk_fma_f32 v[164:165], v[56:57], v[164:165], v[72:73]
	v_pk_fma_f32 v[162:163], v[58:59], v[166:167], v[162:163]
	v_pk_fma_f32 v[164:165], v[60:61], v[168:169], v[164:165]
	v_pk_fma_f32 v[162:163], v[150:151], v[66:67], v[162:163]
	v_pk_fma_f32 v[164:165], v[152:153], v[68:69], v[164:165]
	v_mul_f32_e32 v166, 0x3d372713, v162
	v_mul_f32_e32 v167, 0x3d372713, v163
	v_mul_f32_e32 v166, v162, v166
	v_mul_f32_e32 v167, v163, v167
	v_fma_f32 v166, v162, v166, v162
	v_fma_f32 v167, v163, v167, v163
	v_mul_f32_e32 v166, 0xbfcc422a, v166
	v_mul_f32_e32 v167, 0xbfcc422a, v167
	v_mul_f32_e32 v180, 0x3d372713, v164
	v_mul_f32_e32 v181, 0x3d372713, v165
	v_min_f32_e32 v166, 0x42a00000, v166
	v_min_f32_e32 v167, 0x42a00000, v167
	v_mul_f32_e32 v180, v164, v180
	v_mul_f32_e32 v181, v165, v181
	v_mul_f32_e32 v166, 0x3fb8aa3b, v166
	v_mul_f32_e32 v167, 0x3fb8aa3b, v167
	v_fma_f32 v180, v164, v180, v164
	v_fma_f32 v181, v165, v181, v165
	v_exp_f32_e32 v166, v166
	v_exp_f32_e32 v167, v167
	v_mul_f32_e32 v180, 0xbfcc422a, v180
	v_mul_f32_e32 v181, 0xbfcc422a, v181
	v_min_f32_e32 v180, 0x42a00000, v180
	v_min_f32_e32 v181, 0x42a00000, v181
	v_mul_f32_e32 v180, 0x3fb8aa3b, v180
	v_mul_f32_e32 v181, 0x3fb8aa3b, v181
	v_exp_f32_e32 v180, v180
	v_exp_f32_e32 v181, v181
	v_pk_add_f32 v[166:167], v[166:167], 1.0 op_sel_hi:[1,0]
	v_pk_add_f32 v[180:181], v[180:181], 1.0 op_sel_hi:[1,0]
	v_rcp_f32_e32 v168, v166
	v_rcp_f32_e32 v169, v167
	v_rcp_f32_e32 v220, v180
	v_rcp_f32_e32 v221, v181
	v_pk_fma_f32 v[166:167], v[166:167], v[168:169], 1.0 op_sel_hi:[1,1,0] neg_lo:[1,0,0] neg_hi:[1,0,0]
	s_nop 0
	v_pk_fma_f32 v[166:167], v[168:169], v[166:167], v[168:169]
	s_nop 0
	v_pk_mul_f32 v[162:163], v[162:163], v[166:167]
	v_pk_fma_f32 v[166:167], v[40:41], v[172:173], v[52:53]
	v_pk_mul_f32 v[158:159], v[158:159], v[162:163]
	v_pk_fma_f32 v[162:163], v[180:181], v[220:221], 1.0 op_sel_hi:[1,1,0] neg_lo:[1,0,0] neg_hi:[1,0,0]
	v_cvt_pk_bf16_f32 v158, v158, v159
	v_pk_fma_f32 v[162:163], v[220:221], v[162:163], v[220:221]
	v_pk_fma_f32 v[166:167], v[44:45], v[176:177], v[166:167]
	v_pk_mul_f32 v[162:163], v[164:165], v[162:163]
	v_pk_fma_f32 v[166:167], v[148:149], v[48:49], v[166:167]
	v_pk_mul_f32 v[160:161], v[160:161], v[162:163]
	v_pk_fma_f32 v[162:163], v[38:39], v[170:171], v[50:51]
	s_nop 0
	v_pk_fma_f32 v[162:163], v[42:43], v[174:175], v[162:163]
	s_nop 0
	v_pk_fma_f32 v[162:163], v[146:147], v[46:47], v[162:163]
	s_nop 0
	v_mul_f32_e32 v159, 0x3d372713, v162
	v_mul_f32_e32 v159, v162, v159
	v_fma_f32 v159, v162, v159, v162
	v_mul_f32_e32 v159, 0xbfcc422a, v159
	v_min_f32_e32 v159, 0x42a00000, v159
	v_mul_f32_e32 v159, 0x3fb8aa3b, v159
	v_exp_f32_e32 v164, v159
	v_mul_f32_e32 v159, 0x3d372713, v163
	v_mul_f32_e32 v159, v163, v159
	v_fma_f32 v159, v163, v159, v163
	v_mul_f32_e32 v159, 0xbfcc422a, v159
	v_min_f32_e32 v159, 0x42a00000, v159
	v_mul_f32_e32 v159, 0x3fb8aa3b, v159
	v_exp_f32_e32 v165, v159
	v_mul_f32_e32 v159, 0x3d372713, v166
	v_mul_f32_e32 v159, v166, v159
	v_fma_f32 v159, v166, v159, v166
	v_mul_f32_e32 v159, 0xbfcc422a, v159
	v_min_f32_e32 v159, 0x42a00000, v159
	v_mul_f32_e32 v159, 0x3fb8aa3b, v159
	v_exp_f32_e32 v170, v159
	v_mul_f32_e32 v159, 0x3d372713, v167
	v_mul_f32_e32 v159, v167, v159
	v_fma_f32 v159, v167, v159, v167
	v_mul_f32_e32 v159, 0xbfcc422a, v159
	v_min_f32_e32 v159, 0x42a00000, v159
	v_pk_add_f32 v[164:165], v[164:165], 1.0 op_sel_hi:[1,0]
	v_mul_f32_e32 v159, 0x3fb8aa3b, v159
	v_rcp_f32_e32 v168, v164
	v_rcp_f32_e32 v169, v165
	v_exp_f32_e32 v171, v159
	v_cvt_pk_bf16_f32 v159, v160, v161
	v_pk_fma_f32 v[160:161], v[164:165], v[168:169], 1.0 op_sel_hi:[1,1,0] neg_lo:[1,0,0] neg_hi:[1,0,0]
	v_pk_add_f32 v[164:165], v[170:171], 1.0 op_sel_hi:[1,0]
	v_pk_fma_f32 v[160:161], v[168:169], v[160:161], v[168:169]
	v_rcp_f32_e32 v168, v164
	v_rcp_f32_e32 v169, v165
	v_pk_mul_f32 v[160:161], v[162:163], v[160:161]
	v_pk_fma_f32 v[162:163], v[164:165], v[168:169], 1.0 op_sel_hi:[1,1,0] neg_lo:[1,0,0] neg_hi:[1,0,0]
	s_nop 0
	v_pk_fma_f32 v[162:163], v[168:169], v[162:163], v[168:169]
	v_pk_mul_f32 v[160:161], v[154:155], v[160:161]
	v_pk_mul_f32 v[162:163], v[166:167], v[162:163]
	v_cvt_pk_bf16_f32 v160, v160, v161
	v_pk_mul_f32 v[162:163], v[156:157], v[162:163]
	s_nop 0
	v_cvt_pk_bf16_f32 v161, v162, v163
	v_mad_i64_i32 v[162:163], s[58:59], v201, s79, v[178:179]
	global_store_dwordx4 v[162:163], v[158:161], off sc1
; __device__ __forceinline__ float gelu_tanh(float x) { float z = 1.5957691216057308f * (x + 0.044715f * x * x * x); return x * rcp_nr(1.f + __expf(fminf(-z, 80.f))); }
; __device__ __forceinline__ u32x2 pk4(f32x4 v) { u32x2 r; r.x = pk2(v.x, v.y); r.y = pk2(v.z, v.w); return r; }
; __device__ __forceinline__ f32x4 ror1v(f32x4 v) { return f32x4{dpp_ror1(v.x), dpp_ror1(v.y), dpp_ror1(v.z), dpp_ror1(v.w)}; }
; __device__ __forceinline__ f32x4 ror2v(f32x4 v) { return f32x4{dpp_ror2(v.x), dpp_ror2(v.y), dpp_ror2(v.z), dpp_ror2(v.w)}; }
; template <int EPI>
; __device__ __forceinline__ void epilogue(const Params& p, f32x4 (&acc)[2][2][4][2], const int pm, const int pn, const int wr, const int wc, const int fr, const int fq) {
;     ...
;           } else {
;             const int sidx = row - MP, b = sidx >> 2, tt = sidx & 3;
;             const f32x4 st0 = *(const f32x4*)(p.in[6] + ((size_t)b * 2 + 0) * DFF + j0);
;             const f32x4 st1 = *(const f32x4*)(p.in[6] + ((size_t)b * 2 + 1) * DFF + j0);
;             const f32x4 s1 = ror1v(a0), s2 = ror2v(a0);
;             am1 = (tt >= 1) ? s1 : st1;
;             am2 = (tt >= 2) ? s2 : ((tt == 1) ? st1 : st0);
;             if (tt >= 2) *(f32x4*)(p.out + O_CS + ((size_t)b * 2 + (tt - 2)) * DFF + j0) = a0;
;           }
;           f32x4 h;
;           h.x = gelu_tanh(cb[bj].x + w0[bj].x * am2.x + w1[bj].x * am1.x + w2[bj].x * a0.x) * g.x;
;           h.y = gelu_tanh(cb[bj].y + w0[bj].y * am2.y + w1[bj].y * am1.y + w2[bj].y * a0.y) * g.y;
;           h.z = gelu_tanh(cb[bj].z + w0[bj].z * am2.z + w1[bj].z * am1.z + w2[bj].z * a0.z) * g.z;
;           h.w = gelu_tanh(cb[bj].w + w0[bj].w * am2.w + w1[bj].w * am1.w + w2[bj].w * a0.w) * g.w;
;           ho[bj] = pk4(h);
;           if (defer) {
;             *(f32x4*)(HA0 + ((size_t)(rblk >> 6) * 2 + fr) * DFF + j0) = a0;
;             *(f32x4*)(HG0 + ((size_t)(rblk >> 6) * 2 + fr) * DFF + j0) = g;
.LBB0_989:
	s_andn2_saveexec_b64 s[56:57], s[56:57]
	s_cbranch_execz .LBB0_991
	global_store_dwordx4 v[222:223], v[146:149], off offset:16 sc1
	global_store_dwordx4 v[224:225], v[154:157], off offset:16 sc1
.LBB0_991:
	s_or_b64 exec, exec, s[56:57]
	s_nop 0
	v_add_u32_e32 v154, 0xffffc010, v201
	v_ashrrev_i32_e32 v154, 2, v154
	v_ashrrev_i32_e32 v155, 31, v154
	v_readlane_b32 s80, v244, 14
	v_mad_i64_i32 v[156:157], s[56:57], v154, s77, 0
	v_lshl_add_u64 v[154:155], v[154:155], 1, v[202:203]
	v_readlane_b32 s92, v244, 26
	v_readlane_b32 s93, v244, 27
	v_mad_u64_u32 v[170:171], s[56:57], v154, s78, 0
	s_nop 0
	v_lshl_add_u64 v[168:169], s[92:93], 0, v[156:157]
	v_mad_i32_i24 v171, v155, s78, v171
	s_mov_b64 s[56:57], -1
	s_and_b64 vcc, exec, s[18:19]
	v_lshl_add_u64 v[166:167], v[214:215], 2, v[168:169]
	v_readlane_b32 s81, v244, 15
	v_readlane_b32 s82, v244, 16
	v_readlane_b32 s83, v244, 17
	v_readlane_b32 s84, v244, 18
	v_readlane_b32 s85, v244, 19
	v_readlane_b32 s86, v244, 20
	v_readlane_b32 s87, v244, 21
	v_readlane_b32 s88, v244, 22
	v_readlane_b32 s89, v244, 23
	v_readlane_b32 s90, v244, 24
	v_readlane_b32 s91, v244, 25
	v_readlane_b32 s94, v244, 28
	v_readlane_b32 s95, v244, 29
	s_cbranch_vccnz .LBB0_995
	v_add_co_u32_e32 v158, vcc, 0x2000, v166
	v_mov_b32_e32 v172, 0
	s_nop 0
	v_addc_co_u32_e32 v159, vcc, 0, v167, vcc
	global_load_dwordx4 v[154:157], v[166:167], off
	s_nop 0
	global_load_dwordx4 v[158:161], v[158:159], off offset:3072
	v_mov_b32_e32 v173, 0
	v_mov_b32_e32 v174, 0
	v_mov_b32_e32 v175, 0
	v_mov_b32_e32 v162, 0
	v_mov_b32_e32 v163, 0
	v_mov_b32_e32 v164, 0
	v_mov_b32_e32 v165, 0
	v_mov_b32_dpp v172, v134 row_ror:1 row_mask:0xf bank_mask:0xf
	v_mov_b32_dpp v173, v135 row_ror:1 row_mask:0xf bank_mask:0xf
	v_mov_b32_dpp v174, v136 row_ror:1 row_mask:0xf bank_mask:0xf
	v_mov_b32_dpp v175, v137 row_ror:1 row_mask:0xf bank_mask:0xf
	v_mov_b32_dpp v162, v134 row_ror:2 row_mask:0xf bank_mask:0xf
	v_mov_b32_dpp v163, v135 row_ror:2 row_mask:0xf bank_mask:0xf
	v_mov_b32_dpp v164, v136 row_ror:2 row_mask:0xf bank_mask:0xf
	v_mov_b32_dpp v165, v137 row_ror:2 row_mask:0xf bank_mask:0xf
	s_waitcnt vmcnt(0)
	v_cndmask_b32_e64 v157, v157, v161, s[10:11]
	v_cndmask_b32_e64 v156, v156, v160, s[10:11]
	v_cndmask_b32_e64 v155, v155, v159, s[10:11]
	v_cndmask_b32_e64 v154, v154, v158, s[10:11]
	s_and_saveexec_b64 s[56:57], s[8:9]
	s_cbranch_execz .LBB0_994
	v_lshl_add_u64 v[154:155], s[42:43], 0, v[170:171]
	v_lshl_add_u64 v[154:155], v[214:215], 2, v[154:155]
	global_store_dwordx4 v[154:155], v[134:137], off sc1
	v_mov_b64_e32 v[154:155], v[162:163]
	v_mov_b64_e32 v[156:157], v[164:165]

; __device__ __forceinline__ f32x4 ror1v(f32x4 v) { return f32x4{dpp_ror1(v.x), dpp_ror1(v.y), dpp_ror1(v.z), dpp_ror1(v.w)}; }
; __device__ __forceinline__ f32x4 ror2v(f32x4 v) { return f32x4{dpp_ror2(v.x), dpp_ror2(v.y), dpp_ror2(v.z), dpp_ror2(v.w)}; }
; template <int EPI>
; __device__ __forceinline__ void epilogue(const Params& p, f32x4 (&acc)[2][2][4][2], const int pm, const int pn, const int wr, const int wc, const int fr, const int fq) {
;     ...
;           } else {
;             const int sidx = row - MP, b = sidx >> 2, tt = sidx & 3;
;             const f32x4 st0 = *(const f32x4*)(p.in[6] + ((size_t)b * 2 + 0) * DFF + j0);
;             const f32x4 st1 = *(const f32x4*)(p.in[6] + ((size_t)b * 2 + 1) * DFF + j0);
;             const f32x4 s1 = ror1v(a0), s2 = ror2v(a0);
;             am1 = (tt >= 1) ? s1 : st1;
;             am2 = (tt >= 2) ? s2 : ((tt == 1) ? st1 : st0);
;             if (tt >= 2) *(f32x4*)(p.out + O_CS + ((size_t)b * 2 + (tt - 2)) * DFF + j0) = a0;
.LBB0_997:
	s_and_b64 vcc, exec, s[18:19]
	s_mov_b64 s[56:57], -1
	s_cbranch_vccnz .LBB0_1001
	v_lshl_add_u64 v[150:151], v[216:217], 2, v[168:169]
	v_add_co_u32_e32 v162, vcc, 0x2000, v150
	v_mov_b32_e32 v172, 0
	s_nop 0
	v_addc_co_u32_e32 v163, vcc, 0, v151, vcc
	global_load_dwordx4 v[150:153], v[166:167], off offset:16
	s_nop 0
	global_load_dwordx4 v[162:165], v[162:163], off offset:3072
	v_mov_b32_e32 v173, 0
	v_mov_b32_e32 v174, 0
	v_mov_b32_e32 v175, 0
	v_mov_b32_e32 v166, 0
	v_mov_b32_e32 v167, 0
	v_mov_b32_e32 v168, 0
	v_mov_b32_e32 v169, 0
	v_mov_b32_dpp v172, v130 row_ror:1 row_mask:0xf bank_mask:0xf
	v_mov_b32_dpp v173, v131 row_ror:1 row_mask:0xf bank_mask:0xf
	v_mov_b32_dpp v174, v132 row_ror:1 row_mask:0xf bank_mask:0xf
	v_mov_b32_dpp v175, v133 row_ror:1 row_mask:0xf bank_mask:0xf
	v_mov_b32_dpp v166, v130 row_ror:2 row_mask:0xf bank_mask:0xf
	v_mov_b32_dpp v167, v131 row_ror:2 row_mask:0xf bank_mask:0xf
	v_mov_b32_dpp v168, v132 row_ror:2 row_mask:0xf bank_mask:0xf
	v_mov_b32_dpp v169, v133 row_ror:2 row_mask:0xf bank_mask:0xf
	s_waitcnt vmcnt(0)
	v_cndmask_b32_e64 v153, v153, v165, s[10:11]
	v_cndmask_b32_e64 v152, v152, v164, s[10:11]
	v_cndmask_b32_e64 v151, v151, v163, s[10:11]
	v_cndmask_b32_e64 v150, v150, v162, s[10:11]
	s_and_saveexec_b64 s[56:57], s[8:9]
	s_cbranch_execz .LBB0_1000
	v_lshl_add_u64 v[150:151], s[42:43], 0, v[170:171]
	v_lshl_add_u64 v[150:151], v[214:215], 2, v[150:151]
	global_store_dwordx4 v[150:151], v[130:133], off offset:16 sc1
	v_mov_b64_e32 v[150:151], v[166:167]
	v_mov_b64_e32 v[152:153], v[168:169]

; __device__ __forceinline__ float gelu_tanh(float x) { float z = 1.5957691216057308f * (x + 0.044715f * x * x * x); return x * rcp_nr(1.f + __expf(fminf(-z, 80.f))); }
; __device__ __forceinline__ u32x2 pk4(f32x4 v) { u32x2 r; r.x = pk2(v.x, v.y); r.y = pk2(v.z, v.w); return r; }
; __device__ __forceinline__ f32x4 ror1v(f32x4 v) { return f32x4{dpp_ror1(v.x), dpp_ror1(v.y), dpp_ror1(v.z), dpp_ror1(v.w)}; }
; __device__ __forceinline__ f32x4 ror2v(f32x4 v) { return f32x4{dpp_ror2(v.x), dpp_ror2(v.y), dpp_ror2(v.z), dpp_ror2(v.w)}; }
; template <int EPI>
; __device__ __forceinline__ void epilogue(const Params& p, f32x4 (&acc)[2][2][4][2], const int pm, const int pn, const int wr, const int wc, const int fr, const int fq) {
;     ...
;           } else {
;             const int sidx = row - MP, b = sidx >> 2, tt = sidx & 3;
;             const f32x4 st0 = *(const f32x4*)(p.in[6] + ((size_t)b * 2 + 0) * DFF + j0);
;             const f32x4 st1 = *(const f32x4*)(p.in[6] + ((size_t)b * 2 + 1) * DFF + j0);
;             const f32x4 s1 = ror1v(a0), s2 = ror2v(a0);
;             am1 = (tt >= 1) ? s1 : st1;
;             am2 = (tt >= 2) ? s2 : ((tt == 1) ? st1 : st0);
;             if (tt >= 2) *(f32x4*)(p.out + O_CS + ((size_t)b * 2 + (tt - 2)) * DFF + j0) = a0;
;           }
;           f32x4 h;
;           h.x = gelu_tanh(cb[bj].x + w0[bj].x * am2.x + w1[bj].x * am1.x + w2[bj].x * a0.x) * g.x;
;           h.y = gelu_tanh(cb[bj].y + w0[bj].y * am2.y + w1[bj].y * am1.y + w2[bj].y * a0.y) * g.y;
;           h.z = gelu_tanh(cb[bj].z + w0[bj].z * am2.z + w1[bj].z * am1.z + w2[bj].z * a0.z) * g.z;
;           h.w = gelu_tanh(cb[bj].w + w0[bj].w * am2.w + w1[bj].w * am1.w + w2[bj].w * a0.w) * g.w;
;           ho[bj] = pk4(h);
;           if (defer) {
;             *(f32x4*)(HA0 + ((size_t)(rblk >> 6) * 2 + fr) * DFF + j0) = a0;
;             *(f32x4*)(HG0 + ((size_t)(rblk >> 6) * 2 + fr) * DFF + j0) = g;
;           }
;         }
;         if (!defer) *(u32x4*)(H + (size_t)row * DFF + jb) = u32x4{ho[0].x, ho[0].y, ho[1].x, ho[1].y};
.LBB0_1003:
	v_pk_fma_f32 v[146:147], v[54:55], v[154:155], v[70:71]
	v_pk_fma_f32 v[154:155], v[56:57], v[156:157], v[72:73]
	v_pk_fma_f32 v[146:147], v[58:59], v[158:159], v[146:147]
	v_pk_fma_f32 v[154:155], v[60:61], v[160:161], v[154:155]
	v_pk_fma_f32 v[146:147], v[134:135], v[66:67], v[146:147]
	v_pk_fma_f32 v[154:155], v[136:137], v[68:69], v[154:155]
	v_mul_f32_e32 v148, 0x3d372713, v146
	v_mul_f32_e32 v149, 0x3d372713, v147
	v_mul_f32_e32 v148, v146, v148
	v_mul_f32_e32 v149, v147, v149
	v_fma_f32 v148, v146, v148, v146
	v_fma_f32 v149, v147, v149, v147
	v_mul_f32_e32 v148, 0xbfcc422a, v148
	v_mul_f32_e32 v149, 0xbfcc422a, v149
	v_mul_f32_e32 v158, 0x3d372713, v154
	v_mul_f32_e32 v159, 0x3d372713, v155
	v_min_f32_e32 v148, 0x42a00000, v148
	v_min_f32_e32 v149, 0x42a00000, v149
	v_mul_f32_e32 v158, v154, v158
	v_mul_f32_e32 v159, v155, v159
	v_mul_f32_e32 v148, 0x3fb8aa3b, v148
	v_mul_f32_e32 v149, 0x3fb8aa3b, v149
	v_fma_f32 v158, v154, v158, v154
	v_fma_f32 v159, v155, v159, v155
	v_exp_f32_e32 v148, v148
	v_exp_f32_e32 v149, v149
	v_mul_f32_e32 v158, 0xbfcc422a, v158
	v_mul_f32_e32 v159, 0xbfcc422a, v159
	v_min_f32_e32 v158, 0x42a00000, v158
	v_min_f32_e32 v159, 0x42a00000, v159
	v_mul_f32_e32 v158, 0x3fb8aa3b, v158
	v_mul_f32_e32 v159, 0x3fb8aa3b, v159
	v_exp_f32_e32 v158, v158
	v_exp_f32_e32 v159, v159
	v_pk_add_f32 v[148:149], v[148:149], 1.0 op_sel_hi:[1,0]
	v_readlane_b32 s80, v244, 14
	v_rcp_f32_e32 v156, v148
	v_rcp_f32_e32 v157, v149
	v_pk_add_f32 v[158:159], v[158:159], 1.0 op_sel_hi:[1,0]
	v_readlane_b32 s92, v244, 26
	v_rcp_f32_e32 v160, v158
	v_rcp_f32_e32 v161, v159
	v_pk_fma_f32 v[148:149], v[148:149], v[156:157], 1.0 op_sel_hi:[1,1,0] neg_lo:[1,0,0] neg_hi:[1,0,0]
	v_readlane_b32 s93, v244, 27
	v_pk_fma_f32 v[148:149], v[156:157], v[148:149], v[156:157]
	v_or_b32_e32 v156, 16, v201
	v_pk_mul_f32 v[146:147], v[146:147], v[148:149]
	s_and_b64 vcc, exec, s[18:19]
	v_pk_mul_f32 v[142:143], v[142:143], v[146:147]
	v_pk_fma_f32 v[146:147], v[158:159], v[160:161], 1.0 op_sel_hi:[1,1,0] neg_lo:[1,0,0] neg_hi:[1,0,0]
	v_cvt_pk_bf16_f32 v142, v142, v143
	v_pk_fma_f32 v[146:147], v[160:161], v[146:147], v[160:161]
	v_readlane_b32 s81, v244, 15
	v_pk_mul_f32 v[146:147], v[154:155], v[146:147]
	v_readlane_b32 s82, v244, 16
	v_pk_mul_f32 v[144:145], v[144:145], v[146:147]
	v_pk_fma_f32 v[146:147], v[38:39], v[150:151], v[50:51]
	v_pk_fma_f32 v[150:151], v[40:41], v[152:153], v[52:53]
	v_pk_fma_f32 v[146:147], v[42:43], v[162:163], v[146:147]
	v_pk_fma_f32 v[150:151], v[44:45], v[164:165], v[150:151]
	v_pk_fma_f32 v[146:147], v[130:131], v[46:47], v[146:147]
	v_pk_fma_f32 v[150:151], v[132:133], v[48:49], v[150:151]
	v_mul_f32_e32 v143, 0x3d372713, v146
	v_mul_f32_e32 v143, v146, v143
	v_fma_f32 v143, v146, v143, v146
	v_mul_f32_e32 v143, 0xbfcc422a, v143
	v_min_f32_e32 v143, 0x42a00000, v143
	v_mul_f32_e32 v143, 0x3fb8aa3b, v143
	v_exp_f32_e32 v148, v143
	v_mul_f32_e32 v143, 0x3d372713, v147
	v_mul_f32_e32 v143, v147, v143
	v_fma_f32 v143, v147, v143, v147
	v_mul_f32_e32 v143, 0xbfcc422a, v143
	v_min_f32_e32 v143, 0x42a00000, v143
	v_mul_f32_e32 v143, 0x3fb8aa3b, v143
	v_exp_f32_e32 v149, v143
	v_mul_f32_e32 v143, 0x3d372713, v150
	v_mul_f32_e32 v143, v150, v143
	v_fma_f32 v143, v150, v143, v150
	v_mul_f32_e32 v143, 0xbfcc422a, v143
	v_min_f32_e32 v143, 0x42a00000, v143
	v_mul_f32_e32 v143, 0x3fb8aa3b, v143
	v_exp_f32_e32 v154, v143
	v_mul_f32_e32 v143, 0x3d372713, v151
	v_mul_f32_e32 v143, v151, v143
	v_fma_f32 v143, v151, v143, v151
	v_mul_f32_e32 v143, 0xbfcc422a, v143
	v_min_f32_e32 v143, 0x42a00000, v143
	v_pk_add_f32 v[148:149], v[148:149], 1.0 op_sel_hi:[1,0]
	v_mul_f32_e32 v143, 0x3fb8aa3b, v143
	v_rcp_f32_e32 v152, v148
	v_rcp_f32_e32 v153, v149
	v_exp_f32_e32 v155, v143
	v_cvt_pk_bf16_f32 v143, v144, v145
	v_readlane_b32 s83, v244, 17
	v_pk_fma_f32 v[144:145], v[148:149], v[152:153], 1.0 op_sel_hi:[1,1,0] neg_lo:[1,0,0] neg_hi:[1,0,0]
	v_pk_add_f32 v[148:149], v[154:155], 1.0 op_sel_hi:[1,0]
	v_pk_fma_f32 v[144:145], v[152:153], v[144:145], v[152:153]
	v_rcp_f32_e32 v154, v148
	v_rcp_f32_e32 v155, v149
	v_pk_mul_f32 v[144:145], v[146:147], v[144:145]
	v_readlane_b32 s84, v244, 18
	v_pk_mul_f32 v[138:139], v[138:139], v[144:145]
	v_pk_fma_f32 v[144:145], v[148:149], v[154:155], 1.0 op_sel_hi:[1,1,0] neg_lo:[1,0,0] neg_hi:[1,0,0]
	v_readlane_b32 s85, v244, 19
	v_pk_fma_f32 v[144:145], v[154:155], v[144:145], v[154:155]
	v_readlane_b32 s86, v244, 20
	v_pk_mul_f32 v[144:145], v[150:151], v[144:145]
	v_readlane_b32 s87, v244, 21
	v_pk_mul_f32 v[140:141], v[140:141], v[144:145]
	v_cvt_pk_bf16_f32 v144, v138, v139
	v_cvt_pk_bf16_f32 v145, v140, v141
	v_mad_i64_i32 v[138:139], s[56:57], v156, s79, v[178:179]
	global_store_dwordx4 v[138:139], v[142:145], off sc1
	v_add_u32_e32 v138, 0xffffc020, v201
	v_ashrrev_i32_e32 v138, 2, v138
	v_ashrrev_i32_e32 v139, 31, v138
	v_mad_i64_i32 v[140:141], s[56:57], v138, s77, 0
	v_lshl_add_u64 v[138:139], v[138:139], 1, v[202:203]
	v_mad_u64_u32 v[154:155], s[56:57], v138, s78, 0
	v_lshl_add_u64 v[152:153], s[92:93], 0, v[140:141]
	v_mad_i32_i24 v155, v139, s78, v155
	s_mov_b64 s[56:57], -1
	v_lshl_add_u64 v[150:151], v[214:215], 2, v[152:153]
	v_readlane_b32 s88, v244, 22
	v_readlane_b32 s89, v244, 23
	v_readlane_b32 s90, v244, 24
	v_readlane_b32 s91, v244, 25
	v_readlane_b32 s94, v244, 28
	v_readlane_b32 s95, v244, 29
	s_cbranch_vccnz .LBB0_1007
	v_add_co_u32_e32 v142, vcc, 0x2000, v150
	v_mov_b32_e32 v156, 0
	s_nop 0
	v_addc_co_u32_e32 v143, vcc, 0, v151, vcc
	global_load_dwordx4 v[138:141], v[150:151], off
	s_nop 0
	global_load_dwordx4 v[142:145], v[142:143], off offset:3072
	v_mov_b32_e32 v157, 0
	v_mov_b32_e32 v158, 0
	v_mov_b32_e32 v159, 0
	v_mov_b32_e32 v146, 0
	v_mov_b32_e32 v147, 0
	v_mov_b32_e32 v148, 0
	v_mov_b32_e32 v149, 0
	v_mov_b32_dpp v156, v118 row_ror:1 row_mask:0xf bank_mask:0xf
	v_mov_b32_dpp v157, v119 row_ror:1 row_mask:0xf bank_mask:0xf
	v_mov_b32_dpp v158, v120 row_ror:1 row_mask:0xf bank_mask:0xf
	v_mov_b32_dpp v159, v121 row_ror:1 row_mask:0xf bank_mask:0xf
	v_mov_b32_dpp v146, v118 row_ror:2 row_mask:0xf bank_mask:0xf
	v_mov_b32_dpp v147, v119 row_ror:2 row_mask:0xf bank_mask:0xf
	v_mov_b32_dpp v148, v120 row_ror:2 row_mask:0xf bank_mask:0xf
	v_mov_b32_dpp v149, v121 row_ror:2 row_mask:0xf bank_mask:0xf
	s_waitcnt vmcnt(0)
	v_cndmask_b32_e64 v141, v141, v145, s[10:11]
	v_cndmask_b32_e64 v140, v140, v144, s[10:11]
	v_cndmask_b32_e64 v139, v139, v143, s[10:11]
	v_cndmask_b32_e64 v138, v138, v142, s[10:11]
	s_and_saveexec_b64 s[56:57], s[8:9]
	s_cbranch_execz .LBB0_1006
	v_lshl_add_u64 v[138:139], s[42:43], 0, v[154:155]
	v_lshl_add_u64 v[138:139], v[214:215], 2, v[138:139]
	global_store_dwordx4 v[138:139], v[118:121], off sc1
	v_mov_b64_e32 v[138:139], v[146:147]
	v_mov_b64_e32 v[140:141], v[148:149]

; __device__ __forceinline__ f32x4 ror1v(f32x4 v) { return f32x4{dpp_ror1(v.x), dpp_ror1(v.y), dpp_ror1(v.z), dpp_ror1(v.w)}; }
; __device__ __forceinline__ f32x4 ror2v(f32x4 v) { return f32x4{dpp_ror2(v.x), dpp_ror2(v.y), dpp_ror2(v.z), dpp_ror2(v.w)}; }
; template <int EPI>
; __device__ __forceinline__ void epilogue(const Params& p, f32x4 (&acc)[2][2][4][2], const int pm, const int pn, const int wr, const int wc, const int fr, const int fq) {
;     ...
;           } else {
;             const int sidx = row - MP, b = sidx >> 2, tt = sidx & 3;
;             const f32x4 st0 = *(const f32x4*)(p.in[6] + ((size_t)b * 2 + 0) * DFF + j0);
;             const f32x4 st1 = *(const f32x4*)(p.in[6] + ((size_t)b * 2 + 1) * DFF + j0);
;             const f32x4 s1 = ror1v(a0), s2 = ror2v(a0);
;             am1 = (tt >= 1) ? s1 : st1;
;             am2 = (tt >= 2) ? s2 : ((tt == 1) ? st1 : st0);
;             if (tt >= 2) *(f32x4*)(p.out + O_CS + ((size_t)b * 2 + (tt - 2)) * DFF + j0) = a0;
.LBB0_1009:
	s_and_b64 vcc, exec, s[18:19]
	s_mov_b64 s[56:57], -1
	s_cbranch_vccnz .LBB0_1013
	v_lshl_add_u64 v[134:135], v[216:217], 2, v[152:153]
	v_add_co_u32_e32 v146, vcc, 0x2000, v134
	v_mov_b32_e32 v156, 0
	s_nop 0
	v_addc_co_u32_e32 v147, vcc, 0, v135, vcc
	global_load_dwordx4 v[134:137], v[150:151], off offset:16
	s_nop 0
	global_load_dwordx4 v[146:149], v[146:147], off offset:3072
	v_mov_b32_e32 v157, 0
	v_mov_b32_e32 v158, 0
	v_mov_b32_e32 v159, 0
	v_mov_b32_e32 v150, 0
	v_mov_b32_e32 v151, 0
	v_mov_b32_e32 v152, 0
	v_mov_b32_e32 v153, 0
	v_mov_b32_dpp v156, v114 row_ror:1 row_mask:0xf bank_mask:0xf
	v_mov_b32_dpp v157, v115 row_ror:1 row_mask:0xf bank_mask:0xf
	v_mov_b32_dpp v158, v116 row_ror:1 row_mask:0xf bank_mask:0xf
	v_mov_b32_dpp v159, v117 row_ror:1 row_mask:0xf bank_mask:0xf
	v_mov_b32_dpp v150, v114 row_ror:2 row_mask:0xf bank_mask:0xf
	v_mov_b32_dpp v151, v115 row_ror:2 row_mask:0xf bank_mask:0xf
	v_mov_b32_dpp v152, v116 row_ror:2 row_mask:0xf bank_mask:0xf
	v_mov_b32_dpp v153, v117 row_ror:2 row_mask:0xf bank_mask:0xf
	s_waitcnt vmcnt(0)
	v_cndmask_b32_e64 v137, v137, v149, s[10:11]
	v_cndmask_b32_e64 v136, v136, v148, s[10:11]
	v_cndmask_b32_e64 v135, v135, v147, s[10:11]
	v_cndmask_b32_e64 v134, v134, v146, s[10:11]
	s_and_saveexec_b64 s[56:57], s[8:9]
	s_cbranch_execz .LBB0_1012
	v_lshl_add_u64 v[134:135], s[42:43], 0, v[154:155]
	v_lshl_add_u64 v[134:135], v[214:215], 2, v[134:135]
	global_store_dwordx4 v[134:135], v[114:117], off offset:16 sc1
	v_mov_b64_e32 v[134:135], v[150:151]
	v_mov_b64_e32 v[136:137], v[152:153]

; __device__ __forceinline__ float gelu_tanh(float x) { float z = 1.5957691216057308f * (x + 0.044715f * x * x * x); return x * rcp_nr(1.f + __expf(fminf(-z, 80.f))); }
; __device__ __forceinline__ u32x2 pk4(f32x4 v) { u32x2 r; r.x = pk2(v.x, v.y); r.y = pk2(v.z, v.w); return r; }
; template <int EPI>
; __device__ __forceinline__ void epilogue(const Params& p, f32x4 (&acc)[2][2][4][2], const int pm, const int pn, const int wr, const int wc, const int fr, const int fq) {
;     ...
;           if (prompt) {
;             f32x4 o1 = f32x4{0.f, 0.f, 0.f, 0.f}, o2 = o1;
;             if (m > 0) { o1 = ror1v(acc[ai][bj][m > 0 ? m - 1 : 0][0]); o2 = ror2v(acc[ai][bj][m > 0 ? m - 1 : 0][0]); }
;             am1 = shr1v(o1, a0); am2 = shr2v(o2, a0);
;             if (m == 0 && fr < 2 && (row & 2047) >= 2) defer = true;
;             if (m == 3 && fr >= 14) *(f32x4*)(HA1 + ((size_t)(rblk >> 6) * 2 + (fr - 14)) * DFF + j0) = a0;
;             const int pos = row & 2047;
;             if (pos >= 2046) *(f32x4*)(p.out + O_CP + ((size_t)(row >> 11) * 2 + (pos - 2046)) * DFF + j0) = a0;
;           } else {
;             const int sidx = row - MP, b = sidx >> 2, tt = sidx & 3;
;             const f32x4 st0 = *(const f32x4*)(p.in[6] + ((size_t)b * 2 + 0) * DFF + j0);
;             const f32x4 st1 = *(const f32x4*)(p.in[6] + ((size_t)b * 2 + 1) * DFF + j0);
;             const f32x4 s1 = ror1v(a0), s2 = ror2v(a0);
;             am1 = (tt >= 1) ? s1 : st1;
;             am2 = (tt >= 2) ? s2 : ((tt == 1) ? st1 : st0);
;             if (tt >= 2) *(f32x4*)(p.out + O_CS + ((size_t)b * 2 + (tt - 2)) * DFF + j0) = a0;
;           }
;           f32x4 h;
;           h.x = gelu_tanh(cb[bj].x + w0[bj].x * am2.x + w1[bj].x * am1.x + w2[bj].x * a0.x) * g.x;
;           h.y = gelu_tanh(cb[bj].y + w0[bj].y * am2.y + w1[bj].y * am1.y + w2[bj].y * a0.y) * g.y;
;           h.z = gelu_tanh(cb[bj].z + w0[bj].z * am2.z + w1[bj].z * am1.z + w2[bj].z * a0.z) * g.z;
;           h.w = gelu_tanh(cb[bj].w + w0[bj].w * am2.w + w1[bj].w * am1.w + w2[bj].w * a0.w) * g.w;
;           ho[bj] = pk4(h);
;           if (defer) {
;             *(f32x4*)(HA0 + ((size_t)(rblk >> 6) * 2 + fr) * DFF + j0) = a0;
;             *(f32x4*)(HG0 + ((size_t)(rblk >> 6) * 2 + fr) * DFF + j0) = g;
;           }
;         }
;         if (!defer) *(u32x4*)(H + (size_t)row * DFF + jb) = u32x4{ho[0].x, ho[0].y, ho[1].x, ho[1].y};
.LBB0_1015:
	v_pk_fma_f32 v[130:131], v[54:55], v[138:139], v[70:71]
	v_pk_fma_f32 v[138:139], v[56:57], v[140:141], v[72:73]
	v_pk_fma_f32 v[130:131], v[58:59], v[142:143], v[130:131]
	v_pk_fma_f32 v[138:139], v[60:61], v[144:145], v[138:139]
	v_pk_fma_f32 v[130:131], v[118:119], v[66:67], v[130:131]
	v_pk_fma_f32 v[138:139], v[120:121], v[68:69], v[138:139]
	v_mul_f32_e32 v132, 0x3d372713, v130
	v_mul_f32_e32 v133, 0x3d372713, v131
	v_mul_f32_e32 v132, v130, v132
	v_mul_f32_e32 v133, v131, v133
	v_fma_f32 v132, v130, v132, v130
	v_fma_f32 v133, v131, v133, v131
	v_mul_f32_e32 v132, 0xbfcc422a, v132
	v_mul_f32_e32 v133, 0xbfcc422a, v133
	v_mul_f32_e32 v142, 0x3d372713, v138
	v_mul_f32_e32 v143, 0x3d372713, v139
	v_min_f32_e32 v132, 0x42a00000, v132
	v_min_f32_e32 v133, 0x42a00000, v133
	v_mul_f32_e32 v142, v138, v142
	v_mul_f32_e32 v143, v139, v143
	v_mul_f32_e32 v132, 0x3fb8aa3b, v132
	v_mul_f32_e32 v133, 0x3fb8aa3b, v133
	v_fma_f32 v142, v138, v142, v138
	v_fma_f32 v143, v139, v143, v139
	v_exp_f32_e32 v132, v132
	v_exp_f32_e32 v133, v133
	v_mul_f32_e32 v142, 0xbfcc422a, v142
	v_mul_f32_e32 v143, 0xbfcc422a, v143
	v_min_f32_e32 v142, 0x42a00000, v142
	v_min_f32_e32 v143, 0x42a00000, v143
	v_mul_f32_e32 v142, 0x3fb8aa3b, v142
	v_mul_f32_e32 v143, 0x3fb8aa3b, v143
	v_exp_f32_e32 v142, v142
	v_exp_f32_e32 v143, v143
	v_pk_add_f32 v[132:133], v[132:133], 1.0 op_sel_hi:[1,0]
	v_readlane_b32 s80, v244, 14
	v_rcp_f32_e32 v140, v132
	v_rcp_f32_e32 v141, v133
	v_pk_add_f32 v[142:143], v[142:143], 1.0 op_sel_hi:[1,0]
	v_readlane_b32 s92, v244, 26
	v_rcp_f32_e32 v144, v142
	v_rcp_f32_e32 v145, v143
	v_pk_fma_f32 v[132:133], v[132:133], v[140:141], 1.0 op_sel_hi:[1,1,0] neg_lo:[1,0,0] neg_hi:[1,0,0]
	v_readlane_b32 s93, v244, 27
	v_pk_fma_f32 v[132:133], v[140:141], v[132:133], v[140:141]
	v_or_b32_e32 v140, 32, v201
	v_pk_mul_f32 v[130:131], v[130:131], v[132:133]
	s_and_b64 vcc, exec, s[18:19]
	v_pk_mul_f32 v[126:127], v[126:127], v[130:131]
	v_pk_fma_f32 v[130:131], v[142:143], v[144:145], 1.0 op_sel_hi:[1,1,0] neg_lo:[1,0,0] neg_hi:[1,0,0]
	v_cvt_pk_bf16_f32 v126, v126, v127
	v_pk_fma_f32 v[130:131], v[144:145], v[130:131], v[144:145]
	v_bitop3_b32 v144, v201, s0, 48 bitop3:0xc8
	v_pk_mul_f32 v[130:131], v[138:139], v[130:131]
	v_readlane_b32 s81, v244, 15
	v_pk_mul_f32 v[128:129], v[128:129], v[130:131]
	v_pk_fma_f32 v[130:131], v[38:39], v[134:135], v[50:51]
	v_pk_fma_f32 v[134:135], v[40:41], v[136:137], v[52:53]
	v_pk_fma_f32 v[130:131], v[42:43], v[146:147], v[130:131]
	v_pk_fma_f32 v[134:135], v[44:45], v[148:149], v[134:135]
	v_pk_fma_f32 v[130:131], v[114:115], v[46:47], v[130:131]
	v_pk_fma_f32 v[134:135], v[116:117], v[48:49], v[134:135]
	v_mul_f32_e32 v127, 0x3d372713, v130
	v_mul_f32_e32 v127, v130, v127
	v_fma_f32 v127, v130, v127, v130
	v_mul_f32_e32 v127, 0xbfcc422a, v127
	v_min_f32_e32 v127, 0x42a00000, v127
	v_mul_f32_e32 v127, 0x3fb8aa3b, v127
	v_exp_f32_e32 v132, v127
	v_mul_f32_e32 v127, 0x3d372713, v131
	v_mul_f32_e32 v127, v131, v127
	v_fma_f32 v127, v131, v127, v131
	v_mul_f32_e32 v127, 0xbfcc422a, v127
	v_min_f32_e32 v127, 0x42a00000, v127
	v_mul_f32_e32 v127, 0x3fb8aa3b, v127
	v_exp_f32_e32 v133, v127
	v_mul_f32_e32 v127, 0x3d372713, v134
	v_mul_f32_e32 v127, v134, v127
	v_fma_f32 v127, v134, v127, v134
	v_mul_f32_e32 v127, 0xbfcc422a, v127
	v_min_f32_e32 v127, 0x42a00000, v127
	v_mul_f32_e32 v127, 0x3fb8aa3b, v127
	v_exp_f32_e32 v138, v127
	v_mul_f32_e32 v127, 0x3d372713, v135
	v_mul_f32_e32 v127, v135, v127
	v_fma_f32 v127, v135, v127, v135
	v_mul_f32_e32 v127, 0xbfcc422a, v127
	v_min_f32_e32 v127, 0x42a00000, v127
	v_pk_add_f32 v[132:133], v[132:133], 1.0 op_sel_hi:[1,0]
	v_mul_f32_e32 v127, 0x3fb8aa3b, v127
	v_rcp_f32_e32 v136, v132
	v_rcp_f32_e32 v137, v133
	v_exp_f32_e32 v139, v127
	v_cvt_pk_bf16_f32 v127, v128, v129
	v_readlane_b32 s82, v244, 16
	v_pk_fma_f32 v[128:129], v[132:133], v[136:137], 1.0 op_sel_hi:[1,1,0] neg_lo:[1,0,0] neg_hi:[1,0,0]
	v_pk_add_f32 v[132:133], v[138:139], 1.0 op_sel_hi:[1,0]
	v_pk_fma_f32 v[128:129], v[136:137], v[128:129], v[136:137]
	v_rcp_f32_e32 v138, v132
	v_rcp_f32_e32 v139, v133
	v_pk_mul_f32 v[128:129], v[130:131], v[128:129]
	v_readlane_b32 s83, v244, 17
	v_pk_mul_f32 v[122:123], v[122:123], v[128:129]
	v_pk_fma_f32 v[128:129], v[132:133], v[138:139], 1.0 op_sel_hi:[1,1,0] neg_lo:[1,0,0] neg_hi:[1,0,0]
	v_readlane_b32 s84, v244, 18
	v_pk_fma_f32 v[128:129], v[138:139], v[128:129], v[138:139]
	v_readlane_b32 s85, v244, 19
	v_pk_mul_f32 v[128:129], v[134:135], v[128:129]
	v_readlane_b32 s86, v244, 20
	v_pk_mul_f32 v[124:125], v[124:125], v[128:129]
	v_cvt_pk_bf16_f32 v128, v122, v123
	v_cvt_pk_bf16_f32 v129, v124, v125
	v_mad_i64_i32 v[122:123], s[56:57], v140, s79, v[178:179]
	global_store_dwordx4 v[122:123], v[126:129], off sc1
	v_add_u32_e32 v122, 0xffffc030, v201
	v_ashrrev_i32_e32 v140, 2, v122
	v_mad_i64_i32 v[122:123], s[56:57], v140, s77, 0
	v_lshl_add_u64 v[136:137], s[92:93], 0, v[122:123]
	v_cmp_lt_u32_e64 s[56:57], s1, v144
	v_lshl_add_u64 v[134:135], v[214:215], 2, v[136:137]
	v_readlane_b32 s87, v244, 21
	v_readlane_b32 s88, v244, 22
	v_readlane_b32 s89, v244, 23
	v_readlane_b32 s90, v244, 24
	v_readlane_b32 s91, v244, 25
	v_readlane_b32 s94, v244, 28
	v_readlane_b32 s95, v244, 29
	s_cbranch_vccnz .LBB0_1019
	v_add_co_u32_e32 v126, vcc, 0x2000, v134
	v_mov_b32_e32 v138, 0
	s_nop 0
	v_addc_co_u32_e32 v127, vcc, 0, v135, vcc
	global_load_dwordx4 v[122:125], v[134:135], off
	s_nop 0
	global_load_dwordx4 v[126:129], v[126:127], off offset:3072
	v_mov_b32_e32 v139, 0
	v_mov_b32_e32 v141, 0
	v_mov_b32_e32 v142, 0
	v_mov_b32_e32 v130, 0
	v_mov_b32_e32 v131, 0
	v_mov_b32_e32 v132, 0
	v_mov_b32_e32 v133, 0
	s_mov_b64 s[60:61], 0
	v_mov_b32_dpp v138, v110 row_ror:1 row_mask:0xf bank_mask:0xf
	v_mov_b32_dpp v139, v111 row_ror:1 row_mask:0xf bank_mask:0xf
	v_mov_b32_dpp v141, v112 row_ror:1 row_mask:0xf bank_mask:0xf
	v_mov_b32_dpp v142, v113 row_ror:1 row_mask:0xf bank_mask:0xf
	v_mov_b32_dpp v130, v110 row_ror:2 row_mask:0xf bank_mask:0xf
	v_mov_b32_dpp v131, v111 row_ror:2 row_mask:0xf bank_mask:0xf
	v_mov_b32_dpp v132, v112 row_ror:2 row_mask:0xf bank_mask:0xf
	v_mov_b32_dpp v133, v113 row_ror:2 row_mask:0xf bank_mask:0xf
	s_mov_b64 s[58:59], 0
	s_waitcnt vmcnt(0)
	v_cndmask_b32_e64 v125, v125, v129, s[10:11]
	v_cndmask_b32_e64 v124, v124, v128, s[10:11]
	v_cndmask_b32_e64 v123, v123, v127, s[10:11]
	v_cndmask_b32_e64 v122, v122, v126, s[10:11]
	s_and_saveexec_b64 s[62:63], s[8:9]
	v_mov_b64_e32 v[122:123], v[130:131]
	s_mov_b64 s[58:59], exec
	v_mov_b64_e32 v[124:125], v[132:133]
	s_or_b64 exec, exec, s[62:63]
	v_cndmask_b32_e64 v129, v142, v129, s[6:7]
	v_cndmask_b32_e64 v128, v141, v128, s[6:7]
	v_cndmask_b32_e64 v127, v139, v127, s[6:7]
	v_cndmask_b32_e64 v126, v138, v126, s[6:7]
	s_branch .LBB0_1020

; __device__ __forceinline__ f32x4 shr1v(f32x4 o, f32x4 v) { return f32x4{dpp_shr1_old(o.x, v.x), dpp_shr1_old(o.y, v.y), dpp_shr1_old(o.z, v.z), dpp_shr1_old(o.w, v.w)}; }
; __device__ __forceinline__ f32x4 shr2v(f32x4 o, f32x4 v) { return f32x4{dpp_shr2_old(o.x, v.x), dpp_shr2_old(o.y, v.y), dpp_shr2_old(o.z, v.z), dpp_shr2_old(o.w, v.w)}; }
; __device__ __forceinline__ f32x4 ror1v(f32x4 v) { return f32x4{dpp_ror1(v.x), dpp_ror1(v.y), dpp_ror1(v.z), dpp_ror1(v.w)}; }
; __device__ __forceinline__ f32x4 ror2v(f32x4 v) { return f32x4{dpp_ror2(v.x), dpp_ror2(v.y), dpp_ror2(v.z), dpp_ror2(v.w)}; }
; template <int EPI>
; __device__ __forceinline__ void epilogue(const Params& p, f32x4 (&acc)[2][2][4][2], const int pm, const int pn, const int wr, const int wc, const int fr, const int fq) {
;     ...
;           if (prompt) {
;             f32x4 o1 = f32x4{0.f, 0.f, 0.f, 0.f}, o2 = o1;
;             if (m > 0) { o1 = ror1v(acc[ai][bj][m > 0 ? m - 1 : 0][0]); o2 = ror2v(acc[ai][bj][m > 0 ? m - 1 : 0][0]); }
;             am1 = shr1v(o1, a0); am2 = shr2v(o2, a0);
;             if (m == 0 && fr < 2 && (row & 2047) >= 2) defer = true;
;             if (m == 3 && fr >= 14) *(f32x4*)(HA1 + ((size_t)(rblk >> 6) * 2 + (fr - 14)) * DFF + j0) = a0;
;             const int pos = row & 2047;
;             if (pos >= 2046) *(f32x4*)(p.out + O_CP + ((size_t)(row >> 11) * 2 + (pos - 2046)) * DFF + j0) = a0;
.LBB0_1020:
	v_lshl_add_u64 v[130:131], s[54:55], 0, v[204:205]
	v_mov_b64_e32 v[132:133], s[34:35]
	v_mad_u64_u32 v[138:139], s[54:55], v130, s78, v[132:133]
	v_ashrrev_i32_e32 v141, 31, v140
	v_mad_i32_i24 v139, v131, s78, v139
	s_ashr_i32 s54, s47, 11
	v_lshl_add_u64 v[130:131], v[140:141], 1, v[202:203]
	s_ashr_i32 s55, s54, 31
	v_mad_u64_u32 v[142:143], s[62:63], v130, s78, 0
	v_add_u32_e32 v198, 0xfffff802, v144
	v_mad_i32_i24 v143, v131, s78, v143
	v_lshl_add_u64 v[130:131], s[54:55], 1, v[198:199]
	v_mad_u64_u32 v[140:141], s[54:55], v130, s78, 0
	v_mad_i32_i24 v141, v131, s78, v141
	s_and_b64 vcc, exec, s[60:61]
	s_cbranch_vccz .LBB0_1024
	v_mov_b32_e32 v126, v199
	v_mov_b32_e32 v127, v199
	v_mov_b32_e32 v128, v199
	v_mov_b32_e32 v129, v199
	v_mov_b32_e32 v122, v199
	v_mov_b32_e32 v123, v199
	v_mov_b32_e32 v124, v199
	v_mov_b32_e32 v125, v199
	v_mov_b32_dpp v126, v118 row_ror:1 row_mask:0xf bank_mask:0xf
	v_mov_b32_dpp v127, v119 row_ror:1 row_mask:0xf bank_mask:0xf
	v_mov_b32_dpp v128, v120 row_ror:1 row_mask:0xf bank_mask:0xf
	v_mov_b32_dpp v129, v121 row_ror:1 row_mask:0xf bank_mask:0xf
	v_mov_b32_dpp v122, v118 row_ror:2 row_mask:0xf bank_mask:0xf
	v_mov_b32_dpp v123, v119 row_ror:2 row_mask:0xf bank_mask:0xf
	v_mov_b32_dpp v124, v120 row_ror:2 row_mask:0xf bank_mask:0xf
	v_mov_b32_dpp v125, v121 row_ror:2 row_mask:0xf bank_mask:0xf
	v_mov_b32_dpp v126, v110 row_shr:1 row_mask:0xf bank_mask:0xf
	v_mov_b32_dpp v127, v111 row_shr:1 row_mask:0xf bank_mask:0xf
	v_mov_b32_dpp v128, v112 row_shr:1 row_mask:0xf bank_mask:0xf
	v_mov_b32_dpp v129, v113 row_shr:1 row_mask:0xf bank_mask:0xf
	v_mov_b32_dpp v122, v110 row_shr:2 row_mask:0xf bank_mask:0xf
	v_mov_b32_dpp v123, v111 row_shr:2 row_mask:0xf bank_mask:0xf
	v_mov_b32_dpp v124, v112 row_shr:2 row_mask:0xf bank_mask:0xf
	v_mov_b32_dpp v125, v113 row_shr:2 row_mask:0xf bank_mask:0xf
	s_and_saveexec_b64 s[54:55], s[14:15]
	s_cbranch_execz .LBB0_1023
	v_lshl_add_u64 v[118:119], v[214:215], 2, v[138:139]
	global_store_dwordx4 v[118:119], v[110:113], off sc1

; __device__ __forceinline__ f32x4 ror1v(f32x4 v) { return f32x4{dpp_ror1(v.x), dpp_ror1(v.y), dpp_ror1(v.z), dpp_ror1(v.w)}; }
; __device__ __forceinline__ f32x4 ror2v(f32x4 v) { return f32x4{dpp_ror2(v.x), dpp_ror2(v.y), dpp_ror2(v.z), dpp_ror2(v.w)}; }
; template <int EPI>
; __device__ __forceinline__ void epilogue(const Params& p, f32x4 (&acc)[2][2][4][2], const int pm, const int pn, const int wr, const int wc, const int fr, const int fq) {
;     ...
;             if (m == 3 && fr >= 14) *(f32x4*)(HA1 + ((size_t)(rblk >> 6) * 2 + (fr - 14)) * DFF + j0) = a0;
;             const int pos = row & 2047;
;             if (pos >= 2046) *(f32x4*)(p.out + O_CP + ((size_t)(row >> 11) * 2 + (pos - 2046)) * DFF + j0) = a0;
;           } else {
;             const int sidx = row - MP, b = sidx >> 2, tt = sidx & 3;
;             const f32x4 st0 = *(const f32x4*)(p.in[6] + ((size_t)b * 2 + 0) * DFF + j0);
;             const f32x4 st1 = *(const f32x4*)(p.in[6] + ((size_t)b * 2 + 1) * DFF + j0);
;             const f32x4 s1 = ror1v(a0), s2 = ror2v(a0);
;             am1 = (tt >= 1) ? s1 : st1;
;             am2 = (tt >= 2) ? s2 : ((tt == 1) ? st1 : st0);
;             if (tt >= 2) *(f32x4*)(p.out + O_CS + ((size_t)b * 2 + (tt - 2)) * DFF + j0) = a0;
.LBB0_1025:
	v_readlane_b32 s84, v244, 0
	v_readlane_b32 s85, v244, 1
	s_add_u32 s54, s84, s54
	s_addc_u32 s55, s85, s55
	v_lshl_add_u64 v[118:119], s[54:55], 0, v[118:119]
	v_lshl_add_u64 v[118:119], v[214:215], 2, v[118:119]
	v_readlane_b32 s86, v244, 2
	v_readlane_b32 s87, v244, 3
	global_store_dwordx4 v[118:119], v[110:113], off sc1
.LBB0_1026:
	s_or_b64 exec, exec, s[60:61]
	s_and_b64 vcc, exec, s[18:19]
	s_mov_b64 s[54:55], -1
	s_cbranch_vccnz .LBB0_1030
	v_lshl_add_u64 v[118:119], v[216:217], 2, v[136:137]
	v_add_co_u32_e32 v130, vcc, 0x2000, v118
	v_mov_b32_e32 v144, 0
	s_nop 0
	v_addc_co_u32_e32 v131, vcc, 0, v119, vcc
	global_load_dwordx4 v[118:121], v[134:135], off offset:16
	s_nop 0
	global_load_dwordx4 v[130:133], v[130:131], off offset:3072
	v_mov_b32_e32 v145, 0
	v_mov_b32_e32 v146, 0
	v_mov_b32_e32 v147, 0
	v_mov_b32_e32 v134, 0
	v_mov_b32_e32 v135, 0
	v_mov_b32_e32 v136, 0
	v_mov_b32_e32 v137, 0
	v_mov_b32_dpp v144, v102 row_ror:1 row_mask:0xf bank_mask:0xf
	v_mov_b32_dpp v145, v103 row_ror:1 row_mask:0xf bank_mask:0xf
	v_mov_b32_dpp v146, v104 row_ror:1 row_mask:0xf bank_mask:0xf
	v_mov_b32_dpp v147, v105 row_ror:1 row_mask:0xf bank_mask:0xf
	v_mov_b32_dpp v134, v102 row_ror:2 row_mask:0xf bank_mask:0xf
	v_mov_b32_dpp v135, v103 row_ror:2 row_mask:0xf bank_mask:0xf
	v_mov_b32_dpp v136, v104 row_ror:2 row_mask:0xf bank_mask:0xf
	v_mov_b32_dpp v137, v105 row_ror:2 row_mask:0xf bank_mask:0xf
	s_waitcnt vmcnt(0)
	v_cndmask_b32_e64 v121, v121, v133, s[10:11]
	v_cndmask_b32_e64 v120, v120, v132, s[10:11]
	v_cndmask_b32_e64 v119, v119, v131, s[10:11]
	v_cndmask_b32_e64 v118, v118, v130, s[10:11]
	s_and_saveexec_b64 s[54:55], s[8:9]
	s_cbranch_execz .LBB0_1029
	v_lshl_add_u64 v[118:119], s[42:43], 0, v[142:143]
	v_lshl_add_u64 v[118:119], v[214:215], 2, v[118:119]
	global_store_dwordx4 v[118:119], v[102:105], off offset:16 sc1
	v_mov_b64_e32 v[118:119], v[134:135]
	v_mov_b64_e32 v[120:121], v[136:137]

; __device__ __forceinline__ f32x4 shr1v(f32x4 o, f32x4 v) { return f32x4{dpp_shr1_old(o.x, v.x), dpp_shr1_old(o.y, v.y), dpp_shr1_old(o.z, v.z), dpp_shr1_old(o.w, v.w)}; }
; __device__ __forceinline__ f32x4 shr2v(f32x4 o, f32x4 v) { return f32x4{dpp_shr2_old(o.x, v.x), dpp_shr2_old(o.y, v.y), dpp_shr2_old(o.z, v.z), dpp_shr2_old(o.w, v.w)}; }
; __device__ __forceinline__ f32x4 ror1v(f32x4 v) { return f32x4{dpp_ror1(v.x), dpp_ror1(v.y), dpp_ror1(v.z), dpp_ror1(v.w)}; }
; __device__ __forceinline__ f32x4 ror2v(f32x4 v) { return f32x4{dpp_ror2(v.x), dpp_ror2(v.y), dpp_ror2(v.z), dpp_ror2(v.w)}; }
; template <int EPI>
; __device__ __forceinline__ void epilogue(const Params& p, f32x4 (&acc)[2][2][4][2], const int pm, const int pn, const int wr, const int wc, const int fr, const int fq) {
;     ...
;           if (prompt) {
;             f32x4 o1 = f32x4{0.f, 0.f, 0.f, 0.f}, o2 = o1;
;             if (m > 0) { o1 = ror1v(acc[ai][bj][m > 0 ? m - 1 : 0][0]); o2 = ror2v(acc[ai][bj][m > 0 ? m - 1 : 0][0]); }
;             am1 = shr1v(o1, a0); am2 = shr2v(o2, a0);
;             if (m == 0 && fr < 2 && (row & 2047) >= 2) defer = true;
;             if (m == 3 && fr >= 14) *(f32x4*)(HA1 + ((size_t)(rblk >> 6) * 2 + (fr - 14)) * DFF + j0) = a0;
;             const int pos = row & 2047;
;             if (pos >= 2046) *(f32x4*)(p.out + O_CP + ((size_t)(row >> 11) * 2 + (pos - 2046)) * DFF + j0) = a0;
.LBB0_1031:
	v_mov_b32_e32 v130, v199
	v_mov_b32_e32 v131, v199
	v_mov_b32_e32 v132, v199
	v_mov_b32_e32 v133, v199
	v_mov_b32_e32 v118, v199
	v_mov_b32_e32 v119, v199
	v_mov_b32_e32 v120, v199
	v_mov_b32_e32 v121, v199
	v_mov_b32_dpp v130, v114 row_ror:1 row_mask:0xf bank_mask:0xf
	v_mov_b32_dpp v131, v115 row_ror:1 row_mask:0xf bank_mask:0xf
	v_mov_b32_dpp v132, v116 row_ror:1 row_mask:0xf bank_mask:0xf
	v_mov_b32_dpp v133, v117 row_ror:1 row_mask:0xf bank_mask:0xf
	v_mov_b32_dpp v118, v114 row_ror:2 row_mask:0xf bank_mask:0xf
	v_mov_b32_dpp v119, v115 row_ror:2 row_mask:0xf bank_mask:0xf
	v_mov_b32_dpp v120, v116 row_ror:2 row_mask:0xf bank_mask:0xf
	v_mov_b32_dpp v121, v117 row_ror:2 row_mask:0xf bank_mask:0xf
	v_mov_b32_dpp v130, v102 row_shr:1 row_mask:0xf bank_mask:0xf
	v_mov_b32_dpp v131, v103 row_shr:1 row_mask:0xf bank_mask:0xf
	v_mov_b32_dpp v132, v104 row_shr:1 row_mask:0xf bank_mask:0xf
	v_mov_b32_dpp v133, v105 row_shr:1 row_mask:0xf bank_mask:0xf
	v_mov_b32_dpp v118, v102 row_shr:2 row_mask:0xf bank_mask:0xf
	v_mov_b32_dpp v119, v103 row_shr:2 row_mask:0xf bank_mask:0xf
	v_mov_b32_dpp v120, v104 row_shr:2 row_mask:0xf bank_mask:0xf
	v_mov_b32_dpp v121, v105 row_shr:2 row_mask:0xf bank_mask:0xf
	s_and_saveexec_b64 s[54:55], s[14:15]
	s_cbranch_execz .LBB0_1033
	v_lshl_add_u64 v[114:115], v[214:215], 2, v[138:139]
	global_store_dwordx4 v[114:115], v[102:105], off offset:16 sc1
.LBB0_1033:
	s_or_b64 exec, exec, s[54:55]
	s_and_saveexec_b64 s[54:55], s[56:57]
	s_cbranch_execz .LBB0_1035
	v_lshl_add_u64 v[114:115], s[44:45], 0, v[140:141]
	v_lshl_add_u64 v[114:115], v[214:215], 2, v[114:115]
	global_store_dwordx4 v[114:115], v[102:105], off offset:16 sc1

; template <int EPI>
; __device__ __forceinline__ void epilogue(const Params& p, f32x4 (&acc)[2][2][4][2], const int pm, const int pn, const int wr, const int wc, const int fr, const int fq) {
;     ...
;         for (int bj = 0; bj < 2; ++bj) {
;           const int j0 = jb + bj * 4;
;           const f32x4 a0 = acc[ai][bj][m][0], g = acc[ai][bj][m][1];
;           f32x4 am1, am2;
;           if (prompt) {
;             f32x4 o1 = f32x4{0.f, 0.f, 0.f, 0.f}, o2 = o1;
;             if (m > 0) { o1 = ror1v(acc[ai][bj][m > 0 ? m - 1 : 0][0]); o2 = ror2v(acc[ai][bj][m > 0 ? m - 1 : 0][0]); }
;             am1 = shr1v(o1, a0); am2 = shr2v(o2, a0);
;             if (m == 0 && fr < 2 && (row & 2047) >= 2) defer = true;
;             if (m == 3 && fr >= 14) *(f32x4*)(HA1 + ((size_t)(rblk >> 6) * 2 + (fr - 14)) * DFF + j0) = a0;
;             const int pos = row & 2047;
;             if (pos >= 2046) *(f32x4*)(p.out + O_CP + ((size_t)(row >> 11) * 2 + (pos - 2046)) * DFF + j0) = a0;
;           } else {
;             const int sidx = row - MP, b = sidx >> 2, tt = sidx & 3;
;             const f32x4 st0 = *(const f32x4*)(p.in[6] + ((size_t)b * 2 + 0) * DFF + j0);
;             const f32x4 st1 = *(const f32x4*)(p.in[6] + ((size_t)b * 2 + 1) * DFF + j0);
;             const f32x4 s1 = ror1v(a0), s2 = ror2v(a0);
;             am1 = (tt >= 1) ? s1 : st1;
;             am2 = (tt >= 2) ? s2 : ((tt == 1) ? st1 : st0);
;             if (tt >= 2) *(f32x4*)(p.out + O_CS + ((size_t)b * 2 + (tt - 2)) * DFF + j0) = a0;
;           }
;           f32x4 h;
;           h.x = gelu_tanh(cb[bj].x + w0[bj].x * am2.x + w1[bj].x * am1.x + w2[bj].x * a0.x) * g.x;
;           h.y = gelu_tanh(cb[bj].y + w0[bj].y * am2.y + w1[bj].y * am1.y + w2[bj].y * a0.y) * g.y;
;           h.z = gelu_tanh(cb[bj].z + w0[bj].z * am2.z + w1[bj].z * am1.z + w2[bj].z * a0.z) * g.z;
;           h.w = gelu_tanh(cb[bj].w + w0[bj].w * am2.w + w1[bj].w * am1.w + w2[bj].w * a0.w) * g.w;
;           ho[bj] = pk4(h);
;           if (defer) {
;             *(f32x4*)(HA0 + ((size_t)(rblk >> 6) * 2 + fr) * DFF + j0) = a0;
;             *(f32x4*)(HG0 + ((size_t)(rblk >> 6) * 2 + fr) * DFF + j0) = g;
;           }
;         }
;         if (!defer) *(u32x4*)(H + (size_t)row * DFF + jb) = u32x4{ho[0].x, ho[0].y, ho[1].x, ho[1].y};
.LBB0_1036:
	v_pk_fma_f32 v[116:117], v[54:55], v[122:123], v[70:71]
	v_pk_fma_f32 v[122:123], v[56:57], v[124:125], v[72:73]
	v_pk_fma_f32 v[116:117], v[58:59], v[126:127], v[116:117]
	v_pk_fma_f32 v[122:123], v[60:61], v[128:129], v[122:123]
	v_pk_fma_f32 v[110:111], v[110:111], v[66:67], v[116:117]
	v_pk_fma_f32 v[112:113], v[112:113], v[68:69], v[122:123]
	v_mul_f32_e32 v115, 0x3d372713, v110
	v_mul_f32_e32 v115, v110, v115
	v_fma_f32 v115, v110, v115, v110
	v_mul_f32_e32 v115, 0xbfcc422a, v115
	v_min_f32_e32 v115, 0x42a00000, v115
	v_mul_f32_e32 v115, 0x3fb8aa3b, v115
	v_exp_f32_e32 v116, v115
	v_mul_f32_e32 v115, 0x3d372713, v111
	v_mul_f32_e32 v115, v111, v115
	v_fma_f32 v115, v111, v115, v111
	v_mul_f32_e32 v115, 0xbfcc422a, v115
	v_min_f32_e32 v115, 0x42a00000, v115
	v_mul_f32_e32 v115, 0x3fb8aa3b, v115
	v_exp_f32_e32 v117, v115
	v_mul_f32_e32 v115, 0x3d372713, v112
	v_mul_f32_e32 v115, v112, v115
	v_fma_f32 v115, v112, v115, v112
	v_mul_f32_e32 v115, 0xbfcc422a, v115
	v_min_f32_e32 v115, 0x42a00000, v115
	v_mul_f32_e32 v115, 0x3fb8aa3b, v115
	v_exp_f32_e32 v124, v115
	v_mul_f32_e32 v115, 0x3d372713, v113
	v_mul_f32_e32 v115, v113, v115
	v_fma_f32 v115, v113, v115, v113
	v_mul_f32_e32 v115, 0xbfcc422a, v115
	v_min_f32_e32 v115, 0x42a00000, v115
	v_mul_f32_e32 v115, 0x3fb8aa3b, v115
	v_exp_f32_e32 v125, v115
	v_pk_add_f32 v[116:117], v[116:117], 1.0 op_sel_hi:[1,0]
	v_or_b32_e32 v114, 48, v201
	v_rcp_f32_e32 v122, v116
	v_rcp_f32_e32 v123, v117
	v_pk_add_f32 v[124:125], v[124:125], 1.0 op_sel_hi:[1,0]
	s_addk_i32 s47, 0x80
	v_rcp_f32_e32 v126, v124
	v_rcp_f32_e32 v127, v125
	v_pk_fma_f32 v[116:117], v[116:117], v[122:123], 1.0 op_sel_hi:[1,1,0] neg_lo:[1,0,0] neg_hi:[1,0,0]
	v_readlane_b32 s80, v244, 14
	v_pk_fma_f32 v[116:117], v[122:123], v[116:117], v[122:123]
	s_and_b32 s49, s47, 0x7c0
	v_pk_mul_f32 v[110:111], v[110:111], v[116:117]
	v_readlane_b32 s92, v244, 26
	v_pk_mul_f32 v[106:107], v[106:107], v[110:111]
	v_pk_fma_f32 v[110:111], v[124:125], v[126:127], 1.0 op_sel_hi:[1,1,0] neg_lo:[1,0,0] neg_hi:[1,0,0]
	v_or_b32_e32 v124, s47, v200
	v_pk_fma_f32 v[110:111], v[126:127], v[110:111], v[126:127]
	v_readlane_b32 s93, v244, 27
	v_pk_mul_f32 v[110:111], v[112:113], v[110:111]
	v_pk_fma_f32 v[112:113], v[40:41], v[120:121], v[52:53]
	v_pk_mul_f32 v[108:109], v[108:109], v[110:111]
	v_pk_fma_f32 v[110:111], v[38:39], v[118:119], v[50:51]
	v_pk_fma_f32 v[112:113], v[44:45], v[132:133], v[112:113]
	v_pk_fma_f32 v[110:111], v[42:43], v[130:131], v[110:111]
	v_pk_fma_f32 v[104:105], v[104:105], v[48:49], v[112:113]
	v_pk_fma_f32 v[110:111], v[102:103], v[46:47], v[110:111]
	s_cmp_lg_u32 s49, 0
	v_mul_f32_e32 v102, 0x3d372713, v110
	v_mul_f32_e32 v103, 0x3d372713, v111
	v_mul_f32_e32 v102, v110, v102
	v_mul_f32_e32 v103, v111, v103
	v_fma_f32 v102, v110, v102, v110
	v_fma_f32 v103, v111, v103, v111
	v_mul_f32_e32 v102, 0xbfcc422a, v102
	v_mul_f32_e32 v103, 0xbfcc422a, v103
	v_min_f32_e32 v102, 0x42a00000, v102
	v_min_f32_e32 v103, 0x42a00000, v103
	v_mul_f32_e32 v102, 0x3fb8aa3b, v102
	v_mul_f32_e32 v103, 0x3fb8aa3b, v103
	v_exp_f32_e32 v102, v102
	v_exp_f32_e32 v103, v103
	s_mov_b64 s[58:59], -1
	v_readlane_b32 s81, v244, 15
	v_readlane_b32 s82, v244, 16
	v_pk_add_f32 v[112:113], v[102:103], 1.0 op_sel_hi:[1,0]
	v_mul_f32_e32 v102, 0x3d372713, v104
	v_mul_f32_e32 v102, v104, v102
	v_fma_f32 v102, v104, v102, v104
	v_mul_f32_e32 v102, 0xbfcc422a, v102
	v_min_f32_e32 v102, 0x42a00000, v102
	v_mul_f32_e32 v102, 0x3fb8aa3b, v102
	v_exp_f32_e32 v118, v102
	v_mul_f32_e32 v102, 0x3d372713, v105
	v_mul_f32_e32 v102, v105, v102
	v_fma_f32 v102, v105, v102, v105
	v_mul_f32_e32 v102, 0xbfcc422a, v102
	v_min_f32_e32 v102, 0x42a00000, v102
	v_mul_f32_e32 v102, 0x3fb8aa3b, v102
	v_exp_f32_e32 v119, v102
	v_rcp_f32_e32 v116, v112
	v_rcp_f32_e32 v117, v113
	v_cvt_pk_bf16_f32 v103, v108, v109
	v_pk_add_f32 v[108:109], v[118:119], 1.0 op_sel_hi:[1,0]
	v_cvt_pk_bf16_f32 v102, v106, v107
	v_pk_fma_f32 v[106:107], v[112:113], v[116:117], 1.0 op_sel_hi:[1,1,0] neg_lo:[1,0,0] neg_hi:[1,0,0]
	v_rcp_f32_e32 v112, v108
	v_rcp_f32_e32 v113, v109
	v_pk_fma_f32 v[106:107], v[116:117], v[106:107], v[116:117]
	v_readlane_b32 s83, v244, 17
	v_pk_mul_f32 v[106:107], v[110:111], v[106:107]
	v_readlane_b32 s84, v244, 18
	v_pk_mul_f32 v[98:99], v[98:99], v[106:107]
	v_pk_fma_f32 v[106:107], v[108:109], v[112:113], 1.0 op_sel_hi:[1,1,0] neg_lo:[1,0,0] neg_hi:[1,0,0]
	v_readlane_b32 s85, v244, 19
	v_pk_fma_f32 v[106:107], v[112:113], v[106:107], v[112:113]
	v_readlane_b32 s86, v244, 20
	v_pk_mul_f32 v[104:105], v[104:105], v[106:107]
	v_readlane_b32 s87, v244, 21
	v_pk_mul_f32 v[100:101], v[100:101], v[104:105]
	v_cvt_pk_bf16_f32 v104, v98, v99
	v_cvt_pk_bf16_f32 v105, v100, v101
	v_mad_i64_i32 v[98:99], s[54:55], v114, s79, v[178:179]
	global_store_dwordx4 v[98:99], v[102:105], off sc1
	v_add_u32_e32 v98, 0xffffc000, v124
	v_ashrrev_i32_e32 v98, 2, v98
	v_ashrrev_i32_e32 v99, 31, v98
	v_mad_i64_i32 v[100:101], s[56:57], v98, s77, 0
	v_lshl_add_u64 v[98:99], v[98:99], 1, v[202:203]
	v_mad_u64_u32 v[118:119], s[56:57], v98, s78, 0
	v_lshl_add_u64 v[116:117], s[92:93], 0, v[100:101]
	s_cselect_b64 s[54:55], -1, 0
	v_mad_i32_i24 v119, v99, s78, v119
	s_and_b64 vcc, exec, s[18:19]
	v_lshl_add_u64 v[114:115], v[214:215], 2, v[116:117]
	v_readlane_b32 s88, v244, 22
	v_readlane_b32 s89, v244, 23
	v_readlane_b32 s90, v244, 24
	v_readlane_b32 s91, v244, 25
	v_readlane_b32 s94, v244, 28
	v_readlane_b32 s95, v244, 29
	s_cbranch_vccnz .LBB0_1040
	v_add_co_u32_e32 v102, vcc, 0x2000, v114
	v_mov_b32_e32 v110, 0
	s_nop 0
	v_addc_co_u32_e32 v103, vcc, 0, v115, vcc
	global_load_dwordx4 v[98:101], v[114:115], off
	s_nop 0
	global_load_dwordx4 v[102:105], v[102:103], off offset:3072
	v_mov_b32_e32 v111, 0
	v_mov_b32_e32 v112, 0
	v_mov_b32_e32 v113, 0
	v_mov_b32_e32 v106, 0
	v_mov_b32_e32 v107, 0
	v_mov_b32_e32 v108, 0
	v_mov_b32_e32 v109, 0
	v_mov_b32_dpp v110, v86 row_ror:1 row_mask:0xf bank_mask:0xf
	v_mov_b32_dpp v111, v87 row_ror:1 row_mask:0xf bank_mask:0xf
	v_mov_b32_dpp v112, v88 row_ror:1 row_mask:0xf bank_mask:0xf
	v_mov_b32_dpp v113, v89 row_ror:1 row_mask:0xf bank_mask:0xf
	v_mov_b32_dpp v106, v86 row_ror:2 row_mask:0xf bank_mask:0xf
	v_mov_b32_dpp v107, v87 row_ror:2 row_mask:0xf bank_mask:0xf
	v_mov_b32_dpp v108, v88 row_ror:2 row_mask:0xf bank_mask:0xf
	v_mov_b32_dpp v109, v89 row_ror:2 row_mask:0xf bank_mask:0xf
	s_waitcnt vmcnt(0)
	v_cndmask_b32_e64 v101, v101, v105, s[10:11]
	v_cndmask_b32_e64 v100, v100, v104, s[10:11]
	v_cndmask_b32_e64 v99, v99, v103, s[10:11]
	v_cndmask_b32_e64 v98, v98, v102, s[10:11]
	s_and_saveexec_b64 s[56:57], s[8:9]
	s_cbranch_execz .LBB0_1039
	v_lshl_add_u64 v[98:99], s[42:43], 0, v[118:119]
	v_lshl_add_u64 v[98:99], v[214:215], 2, v[98:99]
	global_store_dwordx4 v[98:99], v[86:89], off sc1
	v_mov_b64_e32 v[98:99], v[106:107]
	v_mov_b64_e32 v[100:101], v[108:109]

; __device__ __forceinline__ float gelu_tanh(float x) { float z = 1.5957691216057308f * (x + 0.044715f * x * x * x); return x * rcp_nr(1.f + __expf(fminf(-z, 80.f))); }
; __device__ __forceinline__ u32x2 pk4(f32x4 v) { u32x2 r; r.x = pk2(v.x, v.y); r.y = pk2(v.z, v.w); return r; }
; template <int EPI>
; __device__ __forceinline__ void epilogue(const Params& p, f32x4 (&acc)[2][2][4][2], const int pm, const int pn, const int wr, const int wc, const int fr, const int fq) {
;     ...
;           if (prompt) {
;             f32x4 o1 = f32x4{0.f, 0.f, 0.f, 0.f}, o2 = o1;
;             if (m > 0) { o1 = ror1v(acc[ai][bj][m > 0 ? m - 1 : 0][0]); o2 = ror2v(acc[ai][bj][m > 0 ? m - 1 : 0][0]); }
;             am1 = shr1v(o1, a0); am2 = shr2v(o2, a0);
;             if (m == 0 && fr < 2 && (row & 2047) >= 2) defer = true;
;             if (m == 3 && fr >= 14) *(f32x4*)(HA1 + ((size_t)(rblk >> 6) * 2 + (fr - 14)) * DFF + j0) = a0;
;             const int pos = row & 2047;
;             if (pos >= 2046) *(f32x4*)(p.out + O_CP + ((size_t)(row >> 11) * 2 + (pos - 2046)) * DFF + j0) = a0;
;           } else {
;             const int sidx = row - MP, b = sidx >> 2, tt = sidx & 3;
;             const f32x4 st0 = *(const f32x4*)(p.in[6] + ((size_t)b * 2 + 0) * DFF + j0);
;             const f32x4 st1 = *(const f32x4*)(p.in[6] + ((size_t)b * 2 + 1) * DFF + j0);
;             const f32x4 s1 = ror1v(a0), s2 = ror2v(a0);
;             am1 = (tt >= 1) ? s1 : st1;
;             am2 = (tt >= 2) ? s2 : ((tt == 1) ? st1 : st0);
;             if (tt >= 2) *(f32x4*)(p.out + O_CS + ((size_t)b * 2 + (tt - 2)) * DFF + j0) = a0;
;           }
;           f32x4 h;
;           h.x = gelu_tanh(cb[bj].x + w0[bj].x * am2.x + w1[bj].x * am1.x + w2[bj].x * a0.x) * g.x;
;           h.y = gelu_tanh(cb[bj].y + w0[bj].y * am2.y + w1[bj].y * am1.y + w2[bj].y * a0.y) * g.y;
;           h.z = gelu_tanh(cb[bj].z + w0[bj].z * am2.z + w1[bj].z * am1.z + w2[bj].z * a0.z) * g.z;
;           h.w = gelu_tanh(cb[bj].w + w0[bj].w * am2.w + w1[bj].w * am1.w + w2[bj].w * a0.w) * g.w;
;           ho[bj] = pk4(h);
;           if (defer) {
;             *(f32x4*)(HA0 + ((size_t)(rblk >> 6) * 2 + fr) * DFF + j0) = a0;
;             *(f32x4*)(HG0 + ((size_t)(rblk >> 6) * 2 + fr) * DFF + j0) = g;
;           }
.LBB0_1042:
	s_ashr_i32 s54, s47, 6
	s_ashr_i32 s55, s54, 31
	s_lshl_b64 s[54:55], s[54:55], 1
	v_add_u32_e32 v110, s54, v200
	v_mov_b64_e32 v[106:107], s[30:31]
	v_mov_b64_e32 v[108:109], s[40:41]
	v_mad_i64_i32 v[106:107], s[60:61], v110, s78, v[106:107]
	v_mad_i64_i32 v[108:109], s[60:61], v110, s78, v[108:109]
	v_lshl_add_u64 v[120:121], v[106:107], 0, v[218:219]
	v_lshl_add_u64 v[122:123], v[108:109], 0, v[218:219]
	s_and_saveexec_b64 s[60:61], s[58:59]
	s_cbranch_execz .LBB0_1044
	global_store_dwordx4 v[120:121], v[86:89], off sc1
	global_store_dwordx4 v[122:123], v[94:97], off sc1
.LBB0_1044:
	s_or_b64 exec, exec, s[60:61]
	s_and_b64 vcc, exec, s[18:19]
	s_mov_b64 s[60:61], -1
	s_cbranch_vccnz .LBB0_1050
	v_lshl_add_u64 v[106:107], v[216:217], 2, v[116:117]
	v_add_co_u32_e32 v110, vcc, 0x2000, v106
	v_mov_b32_e32 v125, 0
	s_nop 0
	v_addc_co_u32_e32 v111, vcc, 0, v107, vcc
	global_load_dwordx4 v[106:109], v[114:115], off offset:16
	s_nop 0
	global_load_dwordx4 v[110:113], v[110:111], off offset:3072
	v_mov_b32_e32 v126, 0
	v_mov_b32_e32 v127, 0
	v_mov_b32_e32 v128, 0
	v_mov_b32_e32 v114, 0
	v_mov_b32_e32 v115, 0
	v_mov_b32_e32 v116, 0
	v_mov_b32_e32 v117, 0
	v_mov_b32_dpp v125, v82 row_ror:1 row_mask:0xf bank_mask:0xf
	v_mov_b32_dpp v126, v83 row_ror:1 row_mask:0xf bank_mask:0xf
	v_mov_b32_dpp v127, v84 row_ror:1 row_mask:0xf bank_mask:0xf
	v_mov_b32_dpp v128, v85 row_ror:1 row_mask:0xf bank_mask:0xf
	v_mov_b32_dpp v114, v82 row_ror:2 row_mask:0xf bank_mask:0xf
	v_mov_b32_dpp v115, v83 row_ror:2 row_mask:0xf bank_mask:0xf
	v_mov_b32_dpp v116, v84 row_ror:2 row_mask:0xf bank_mask:0xf
	v_mov_b32_dpp v117, v85 row_ror:2 row_mask:0xf bank_mask:0xf
	s_waitcnt vmcnt(0)
	v_cndmask_b32_e64 v109, v109, v113, s[10:11]
	v_cndmask_b32_e64 v108, v108, v112, s[10:11]
	v_cndmask_b32_e64 v107, v107, v111, s[10:11]
	v_cndmask_b32_e64 v106, v106, v110, s[10:11]
	s_and_saveexec_b64 s[60:61], s[8:9]
	s_cbranch_execz .LBB0_1047
	v_lshl_add_u64 v[106:107], s[42:43], 0, v[118:119]
	v_lshl_add_u64 v[106:107], v[214:215], 2, v[106:107]
	global_store_dwordx4 v[106:107], v[82:85], off offset:16 sc1
	v_mov_b64_e32 v[106:107], v[114:115]
	v_mov_b64_e32 v[108:109], v[116:117]

; __device__ __forceinline__ float gelu_tanh(float x) { float z = 1.5957691216057308f * (x + 0.044715f * x * x * x); return x * rcp_nr(1.f + __expf(fminf(-z, 80.f))); }
; __device__ __forceinline__ u32x2 pk4(f32x4 v) { u32x2 r; r.x = pk2(v.x, v.y); r.y = pk2(v.z, v.w); return r; }
; template <int EPI>
; __device__ __forceinline__ void epilogue(const Params& p, f32x4 (&acc)[2][2][4][2], const int pm, const int pn, const int wr, const int wc, const int fr, const int fq) {
;     ...
;           f32x4 h;
;           h.x = gelu_tanh(cb[bj].x + w0[bj].x * am2.x + w1[bj].x * am1.x + w2[bj].x * a0.x) * g.x;
;           h.y = gelu_tanh(cb[bj].y + w0[bj].y * am2.y + w1[bj].y * am1.y + w2[bj].y * a0.y) * g.y;
;           h.z = gelu_tanh(cb[bj].z + w0[bj].z * am2.z + w1[bj].z * am1.z + w2[bj].z * a0.z) * g.z;
;           h.w = gelu_tanh(cb[bj].w + w0[bj].w * am2.w + w1[bj].w * am1.w + w2[bj].w * a0.w) * g.w;
;           ho[bj] = pk4(h);
;           if (defer) {
;             *(f32x4*)(HA0 + ((size_t)(rblk >> 6) * 2 + fr) * DFF + j0) = a0;
;             *(f32x4*)(HG0 + ((size_t)(rblk >> 6) * 2 + fr) * DFF + j0) = g;
;           }
;         }
;         if (!defer) *(u32x4*)(H + (size_t)row * DFF + jb) = u32x4{ho[0].x, ho[0].y, ho[1].x, ho[1].y};
.LBB0_1049:
	v_pk_fma_f32 v[98:99], v[54:55], v[98:99], v[70:71]
	v_pk_fma_f32 v[100:101], v[56:57], v[100:101], v[72:73]
	v_pk_fma_f32 v[98:99], v[58:59], v[102:103], v[98:99]
	v_pk_fma_f32 v[100:101], v[60:61], v[104:105], v[100:101]
	v_pk_fma_f32 v[98:99], v[86:87], v[66:67], v[98:99]
	v_pk_fma_f32 v[100:101], v[88:89], v[68:69], v[100:101]
	v_mul_f32_e32 v102, 0x3d372713, v98
	v_mul_f32_e32 v103, 0x3d372713, v99
	v_mul_f32_e32 v102, v98, v102
	v_mul_f32_e32 v103, v99, v103
	v_fma_f32 v102, v98, v102, v98
	v_fma_f32 v103, v99, v103, v99
	v_mul_f32_e32 v102, 0xbfcc422a, v102
	v_mul_f32_e32 v103, 0xbfcc422a, v103
	v_mul_f32_e32 v114, 0x3d372713, v100
	v_mul_f32_e32 v115, 0x3d372713, v101
	v_min_f32_e32 v102, 0x42a00000, v102
	v_min_f32_e32 v103, 0x42a00000, v103
	v_mul_f32_e32 v114, v100, v114
	v_mul_f32_e32 v115, v101, v115
	v_mul_f32_e32 v102, 0x3fb8aa3b, v102
	v_mul_f32_e32 v103, 0x3fb8aa3b, v103
	v_fma_f32 v114, v100, v114, v100
	v_fma_f32 v115, v101, v115, v101
	v_exp_f32_e32 v102, v102
	v_exp_f32_e32 v103, v103
	v_mul_f32_e32 v114, 0xbfcc422a, v114
	v_mul_f32_e32 v115, 0xbfcc422a, v115
	v_min_f32_e32 v114, 0x42a00000, v114
	v_min_f32_e32 v115, 0x42a00000, v115
	v_mul_f32_e32 v114, 0x3fb8aa3b, v114
	v_mul_f32_e32 v115, 0x3fb8aa3b, v115
	v_exp_f32_e32 v114, v114
	v_exp_f32_e32 v115, v115
	v_pk_add_f32 v[102:103], v[102:103], 1.0 op_sel_hi:[1,0]
	v_pk_add_f32 v[114:115], v[114:115], 1.0 op_sel_hi:[1,0]
	v_rcp_f32_e32 v104, v102
	v_rcp_f32_e32 v105, v103
	v_rcp_f32_e32 v116, v114
	v_rcp_f32_e32 v117, v115
	v_pk_fma_f32 v[102:103], v[102:103], v[104:105], 1.0 op_sel_hi:[1,1,0] neg_lo:[1,0,0] neg_hi:[1,0,0]
	s_nop 0
	v_pk_fma_f32 v[102:103], v[104:105], v[102:103], v[104:105]
	s_nop 0
	v_pk_mul_f32 v[98:99], v[98:99], v[102:103]
	v_pk_fma_f32 v[102:103], v[40:41], v[108:109], v[52:53]
	v_pk_mul_f32 v[94:95], v[94:95], v[98:99]
	v_pk_fma_f32 v[98:99], v[114:115], v[116:117], 1.0 op_sel_hi:[1,1,0] neg_lo:[1,0,0] neg_hi:[1,0,0]
	v_cvt_pk_bf16_f32 v94, v94, v95
	v_pk_fma_f32 v[98:99], v[116:117], v[98:99], v[116:117]
	v_pk_fma_f32 v[102:103], v[44:45], v[112:113], v[102:103]
	v_pk_mul_f32 v[98:99], v[100:101], v[98:99]
	v_pk_fma_f32 v[102:103], v[84:85], v[48:49], v[102:103]
	v_pk_mul_f32 v[96:97], v[96:97], v[98:99]
	v_pk_fma_f32 v[98:99], v[38:39], v[106:107], v[50:51]
	s_nop 0
	v_pk_fma_f32 v[98:99], v[42:43], v[110:111], v[98:99]
	s_nop 0
	v_pk_fma_f32 v[98:99], v[82:83], v[46:47], v[98:99]
	s_nop 0
	v_mul_f32_e32 v95, 0x3d372713, v98
	v_mul_f32_e32 v95, v98, v95
	v_fma_f32 v95, v98, v95, v98
	v_mul_f32_e32 v95, 0xbfcc422a, v95
	v_min_f32_e32 v95, 0x42a00000, v95
	v_mul_f32_e32 v95, 0x3fb8aa3b, v95
	v_exp_f32_e32 v100, v95
	v_mul_f32_e32 v95, 0x3d372713, v99
	v_mul_f32_e32 v95, v99, v95
	v_fma_f32 v95, v99, v95, v99
	v_mul_f32_e32 v95, 0xbfcc422a, v95
	v_min_f32_e32 v95, 0x42a00000, v95
	v_mul_f32_e32 v95, 0x3fb8aa3b, v95
	v_exp_f32_e32 v101, v95
	v_mul_f32_e32 v95, 0x3d372713, v102
	v_mul_f32_e32 v95, v102, v95
	v_fma_f32 v95, v102, v95, v102
	v_mul_f32_e32 v95, 0xbfcc422a, v95
	v_min_f32_e32 v95, 0x42a00000, v95
	v_mul_f32_e32 v95, 0x3fb8aa3b, v95
	v_exp_f32_e32 v106, v95
	v_mul_f32_e32 v95, 0x3d372713, v103
	v_mul_f32_e32 v95, v103, v95
	v_fma_f32 v95, v103, v95, v103
	v_mul_f32_e32 v95, 0xbfcc422a, v95
	v_min_f32_e32 v95, 0x42a00000, v95
	v_pk_add_f32 v[100:101], v[100:101], 1.0 op_sel_hi:[1,0]
	v_mul_f32_e32 v95, 0x3fb8aa3b, v95
	v_rcp_f32_e32 v104, v100
	v_rcp_f32_e32 v105, v101
	v_exp_f32_e32 v107, v95
	v_cvt_pk_bf16_f32 v95, v96, v97
	v_pk_fma_f32 v[96:97], v[100:101], v[104:105], 1.0 op_sel_hi:[1,1,0] neg_lo:[1,0,0] neg_hi:[1,0,0]
	v_pk_add_f32 v[100:101], v[106:107], 1.0 op_sel_hi:[1,0]
	v_pk_fma_f32 v[96:97], v[104:105], v[96:97], v[104:105]
	v_rcp_f32_e32 v104, v100
	v_rcp_f32_e32 v105, v101
	v_pk_mul_f32 v[96:97], v[98:99], v[96:97]
	v_pk_fma_f32 v[98:99], v[100:101], v[104:105], 1.0 op_sel_hi:[1,1,0] neg_lo:[1,0,0] neg_hi:[1,0,0]
	s_nop 0
	v_pk_fma_f32 v[98:99], v[104:105], v[98:99], v[104:105]
	v_pk_mul_f32 v[96:97], v[90:91], v[96:97]
	v_pk_mul_f32 v[98:99], v[102:103], v[98:99]
	v_cvt_pk_bf16_f32 v96, v96, v97
	v_pk_mul_f32 v[98:99], v[92:93], v[98:99]
	s_nop 0
	v_cvt_pk_bf16_f32 v97, v98, v99
	v_mad_i64_i32 v[98:99], s[58:59], v124, s79, v[178:179]
	global_store_dwordx4 v[98:99], v[94:97], off sc1
	s_andn2_saveexec_b64 s[56:57], s[56:57]
	s_cbranch_execnz .LBB0_1053
	s_branch .LBB0_1054

; __device__ __forceinline__ f32x4 ror1v(f32x4 v) { return f32x4{dpp_ror1(v.x), dpp_ror1(v.y), dpp_ror1(v.z), dpp_ror1(v.w)}; }
; __device__ __forceinline__ f32x4 ror2v(f32x4 v) { return f32x4{dpp_ror2(v.x), dpp_ror2(v.y), dpp_ror2(v.z), dpp_ror2(v.w)}; }
; template <int EPI>
; __device__ __forceinline__ void epilogue(const Params& p, f32x4 (&acc)[2][2][4][2], const int pm, const int pn, const int wr, const int wc, const int fr, const int fq) {
;     ...
;             const int sidx = row - MP, b = sidx >> 2, tt = sidx & 3;
;             const f32x4 st0 = *(const f32x4*)(p.in[6] + ((size_t)b * 2 + 0) * DFF + j0);
;             const f32x4 st1 = *(const f32x4*)(p.in[6] + ((size_t)b * 2 + 1) * DFF + j0);
;             const f32x4 s1 = ror1v(a0), s2 = ror2v(a0);
;             am1 = (tt >= 1) ? s1 : st1;
;             am2 = (tt >= 2) ? s2 : ((tt == 1) ? st1 : st0);
;             if (tt >= 2) *(f32x4*)(p.out + O_CS + ((size_t)b * 2 + (tt - 2)) * DFF + j0) = a0;
;     ...
;           if (defer) {
;             *(f32x4*)(HA0 + ((size_t)(rblk >> 6) * 2 + fr) * DFF + j0) = a0;
;             *(f32x4*)(HG0 + ((size_t)(rblk >> 6) * 2 + fr) * DFF + j0) = g;
;           }
;         }
;         if (!defer) *(u32x4*)(H + (size_t)row * DFF + jb) = u32x4{ho[0].x, ho[0].y, ho[1].x, ho[1].y};
.LBB0_1053:
	global_store_dwordx4 v[120:121], v[82:85], off offset:16 sc1
	global_store_dwordx4 v[122:123], v[90:93], off offset:16 sc1
.LBB0_1054:
	s_or_b64 exec, exec, s[56:57]
	s_nop 0
	v_add_u32_e32 v90, 0xffffc010, v124
	v_ashrrev_i32_e32 v90, 2, v90
	v_ashrrev_i32_e32 v91, 31, v90
	v_readlane_b32 s80, v244, 14
	v_mad_i64_i32 v[92:93], s[56:57], v90, s77, 0
	v_lshl_add_u64 v[90:91], v[90:91], 1, v[202:203]
	v_readlane_b32 s92, v244, 26
	v_readlane_b32 s93, v244, 27
	v_mad_u64_u32 v[106:107], s[56:57], v90, s78, 0
	s_nop 0
	v_lshl_add_u64 v[104:105], s[92:93], 0, v[92:93]
	v_mad_i32_i24 v107, v91, s78, v107
	s_mov_b64 s[56:57], -1
	s_and_b64 vcc, exec, s[18:19]
	v_lshl_add_u64 v[102:103], v[214:215], 2, v[104:105]
	v_readlane_b32 s81, v244, 15
	v_readlane_b32 s82, v244, 16
	v_readlane_b32 s83, v244, 17
	v_readlane_b32 s84, v244, 18
	v_readlane_b32 s85, v244, 19
	v_readlane_b32 s86, v244, 20
	v_readlane_b32 s87, v244, 21
	v_readlane_b32 s88, v244, 22
	v_readlane_b32 s89, v244, 23
	v_readlane_b32 s90, v244, 24
	v_readlane_b32 s91, v244, 25
	v_readlane_b32 s94, v244, 28
	v_readlane_b32 s95, v244, 29
	s_cbranch_vccnz .LBB0_1058
	v_add_co_u32_e32 v94, vcc, 0x2000, v102
	v_mov_b32_e32 v108, 0
	s_nop 0
	v_addc_co_u32_e32 v95, vcc, 0, v103, vcc
	global_load_dwordx4 v[90:93], v[102:103], off
	s_nop 0
	global_load_dwordx4 v[94:97], v[94:95], off offset:3072
	v_mov_b32_e32 v109, 0
	v_mov_b32_e32 v110, 0
	v_mov_b32_e32 v111, 0
	v_mov_b32_e32 v98, 0
	v_mov_b32_e32 v99, 0
	v_mov_b32_e32 v100, 0
	v_mov_b32_e32 v101, 0
	v_mov_b32_dpp v108, v62 row_ror:1 row_mask:0xf bank_mask:0xf
	v_mov_b32_dpp v109, v63 row_ror:1 row_mask:0xf bank_mask:0xf
	v_mov_b32_dpp v110, v64 row_ror:1 row_mask:0xf bank_mask:0xf
	v_mov_b32_dpp v111, v65 row_ror:1 row_mask:0xf bank_mask:0xf
	v_mov_b32_dpp v98, v62 row_ror:2 row_mask:0xf bank_mask:0xf
	v_mov_b32_dpp v99, v63 row_ror:2 row_mask:0xf bank_mask:0xf
	v_mov_b32_dpp v100, v64 row_ror:2 row_mask:0xf bank_mask:0xf
	v_mov_b32_dpp v101, v65 row_ror:2 row_mask:0xf bank_mask:0xf
	s_waitcnt vmcnt(0)
	v_cndmask_b32_e64 v93, v93, v97, s[10:11]
	v_cndmask_b32_e64 v92, v92, v96, s[10:11]
	v_cndmask_b32_e64 v91, v91, v95, s[10:11]
	v_cndmask_b32_e64 v90, v90, v94, s[10:11]
	s_and_saveexec_b64 s[56:57], s[8:9]
	s_cbranch_execz .LBB0_1057
	v_lshl_add_u64 v[90:91], s[42:43], 0, v[106:107]
	v_lshl_add_u64 v[90:91], v[214:215], 2, v[90:91]
	global_store_dwordx4 v[90:91], v[62:65], off sc1
	v_mov_b64_e32 v[90:91], v[98:99]
	v_mov_b64_e32 v[92:93], v[100:101]

; __device__ __forceinline__ f32x4 ror1v(f32x4 v) { return f32x4{dpp_ror1(v.x), dpp_ror1(v.y), dpp_ror1(v.z), dpp_ror1(v.w)}; }
; __device__ __forceinline__ f32x4 ror2v(f32x4 v) { return f32x4{dpp_ror2(v.x), dpp_ror2(v.y), dpp_ror2(v.z), dpp_ror2(v.w)}; }
; template <int EPI>
; __device__ __forceinline__ void epilogue(const Params& p, f32x4 (&acc)[2][2][4][2], const int pm, const int pn, const int wr, const int wc, const int fr, const int fq) {
;     ...
;             const int sidx = row - MP, b = sidx >> 2, tt = sidx & 3;
;             const f32x4 st0 = *(const f32x4*)(p.in[6] + ((size_t)b * 2 + 0) * DFF + j0);
;             const f32x4 st1 = *(const f32x4*)(p.in[6] + ((size_t)b * 2 + 1) * DFF + j0);
;             const f32x4 s1 = ror1v(a0), s2 = ror2v(a0);
;             am1 = (tt >= 1) ? s1 : st1;
;             am2 = (tt >= 2) ? s2 : ((tt == 1) ? st1 : st0);
;             if (tt >= 2) *(f32x4*)(p.out + O_CS + ((size_t)b * 2 + (tt - 2)) * DFF + j0) = a0;
.LBB0_1060:
	s_and_b64 vcc, exec, s[18:19]
	s_mov_b64 s[56:57], -1
	s_cbranch_vccnz .LBB0_1064
	v_lshl_add_u64 v[86:87], v[216:217], 2, v[104:105]
	v_add_co_u32_e32 v98, vcc, 0x2000, v86
	v_mov_b32_e32 v108, 0
	s_nop 0
	v_addc_co_u32_e32 v99, vcc, 0, v87, vcc
	global_load_dwordx4 v[86:89], v[102:103], off offset:16
	s_nop 0
	global_load_dwordx4 v[98:101], v[98:99], off offset:3072
	v_mov_b32_e32 v109, 0
	v_mov_b32_e32 v110, 0
	v_mov_b32_e32 v111, 0
	v_mov_b32_e32 v102, 0
	v_mov_b32_e32 v103, 0
	v_mov_b32_e32 v104, 0
	v_mov_b32_e32 v105, 0
	v_mov_b32_dpp v108, v34 row_ror:1 row_mask:0xf bank_mask:0xf
	v_mov_b32_dpp v109, v35 row_ror:1 row_mask:0xf bank_mask:0xf
	v_mov_b32_dpp v110, v36 row_ror:1 row_mask:0xf bank_mask:0xf
	v_mov_b32_dpp v111, v37 row_ror:1 row_mask:0xf bank_mask:0xf
	v_mov_b32_dpp v102, v34 row_ror:2 row_mask:0xf bank_mask:0xf
	v_mov_b32_dpp v103, v35 row_ror:2 row_mask:0xf bank_mask:0xf
	v_mov_b32_dpp v104, v36 row_ror:2 row_mask:0xf bank_mask:0xf
	v_mov_b32_dpp v105, v37 row_ror:2 row_mask:0xf bank_mask:0xf
	s_waitcnt vmcnt(0)
	v_cndmask_b32_e64 v89, v89, v101, s[10:11]
	v_cndmask_b32_e64 v88, v88, v100, s[10:11]
	v_cndmask_b32_e64 v87, v87, v99, s[10:11]
	v_cndmask_b32_e64 v86, v86, v98, s[10:11]
	s_and_saveexec_b64 s[56:57], s[8:9]
	s_cbranch_execz .LBB0_1063
	v_lshl_add_u64 v[86:87], s[42:43], 0, v[106:107]
	v_lshl_add_u64 v[86:87], v[214:215], 2, v[86:87]
	global_store_dwordx4 v[86:87], v[34:37], off offset:16 sc1
	v_mov_b64_e32 v[86:87], v[102:103]
	v_mov_b64_e32 v[88:89], v[104:105]

; __device__ __forceinline__ float gelu_tanh(float x) { float z = 1.5957691216057308f * (x + 0.044715f * x * x * x); return x * rcp_nr(1.f + __expf(fminf(-z, 80.f))); }
; __device__ __forceinline__ u32x2 pk4(f32x4 v) { u32x2 r; r.x = pk2(v.x, v.y); r.y = pk2(v.z, v.w); return r; }
; template <int EPI>
; __device__ __forceinline__ void epilogue(const Params& p, f32x4 (&acc)[2][2][4][2], const int pm, const int pn, const int wr, const int wc, const int fr, const int fq) {
;     ...
;           f32x4 h;
;           h.x = gelu_tanh(cb[bj].x + w0[bj].x * am2.x + w1[bj].x * am1.x + w2[bj].x * a0.x) * g.x;
;           h.y = gelu_tanh(cb[bj].y + w0[bj].y * am2.y + w1[bj].y * am1.y + w2[bj].y * a0.y) * g.y;
;           h.z = gelu_tanh(cb[bj].z + w0[bj].z * am2.z + w1[bj].z * am1.z + w2[bj].z * a0.z) * g.z;
;           h.w = gelu_tanh(cb[bj].w + w0[bj].w * am2.w + w1[bj].w * am1.w + w2[bj].w * a0.w) * g.w;
;           ho[bj] = pk4(h);
;           if (defer) {
;             *(f32x4*)(HA0 + ((size_t)(rblk >> 6) * 2 + fr) * DFF + j0) = a0;
;             *(f32x4*)(HG0 + ((size_t)(rblk >> 6) * 2 + fr) * DFF + j0) = g;
;           }
;         }
;         if (!defer) *(u32x4*)(H + (size_t)row * DFF + jb) = u32x4{ho[0].x, ho[0].y, ho[1].x, ho[1].y};
.LBB0_1066:
	v_pk_fma_f32 v[82:83], v[54:55], v[90:91], v[70:71]
	v_pk_fma_f32 v[90:91], v[56:57], v[92:93], v[72:73]
	v_pk_fma_f32 v[82:83], v[58:59], v[94:95], v[82:83]
	v_pk_fma_f32 v[90:91], v[60:61], v[96:97], v[90:91]
	v_pk_fma_f32 v[82:83], v[62:63], v[66:67], v[82:83]
	v_pk_fma_f32 v[90:91], v[64:65], v[68:69], v[90:91]
	v_mul_f32_e32 v84, 0x3d372713, v82
	v_mul_f32_e32 v85, 0x3d372713, v83
	v_mul_f32_e32 v84, v82, v84
	v_mul_f32_e32 v85, v83, v85
	v_fma_f32 v84, v82, v84, v82
	v_fma_f32 v85, v83, v85, v83
	v_mul_f32_e32 v84, 0xbfcc422a, v84
	v_mul_f32_e32 v85, 0xbfcc422a, v85
	v_mul_f32_e32 v94, 0x3d372713, v90
	v_mul_f32_e32 v95, 0x3d372713, v91
	v_min_f32_e32 v84, 0x42a00000, v84
	v_min_f32_e32 v85, 0x42a00000, v85
	v_mul_f32_e32 v94, v90, v94
	v_mul_f32_e32 v95, v91, v95
	v_mul_f32_e32 v84, 0x3fb8aa3b, v84
	v_mul_f32_e32 v85, 0x3fb8aa3b, v85
	v_fma_f32 v94, v90, v94, v90
	v_fma_f32 v95, v91, v95, v91
	v_exp_f32_e32 v84, v84
	v_exp_f32_e32 v85, v85
	v_mul_f32_e32 v94, 0xbfcc422a, v94
	v_mul_f32_e32 v95, 0xbfcc422a, v95
	v_min_f32_e32 v94, 0x42a00000, v94
	v_min_f32_e32 v95, 0x42a00000, v95
	v_mul_f32_e32 v94, 0x3fb8aa3b, v94
	v_mul_f32_e32 v95, 0x3fb8aa3b, v95
	v_exp_f32_e32 v94, v94
	v_exp_f32_e32 v95, v95
	v_pk_add_f32 v[84:85], v[84:85], 1.0 op_sel_hi:[1,0]
	v_readlane_b32 s80, v244, 14
	v_rcp_f32_e32 v92, v84
	v_rcp_f32_e32 v93, v85
	v_pk_add_f32 v[94:95], v[94:95], 1.0 op_sel_hi:[1,0]
	v_readlane_b32 s92, v244, 26
	v_rcp_f32_e32 v96, v94
	v_rcp_f32_e32 v97, v95
	v_pk_fma_f32 v[84:85], v[84:85], v[92:93], 1.0 op_sel_hi:[1,1,0] neg_lo:[1,0,0] neg_hi:[1,0,0]
	v_readlane_b32 s93, v244, 27
	v_pk_fma_f32 v[84:85], v[92:93], v[84:85], v[92:93]
	v_or_b32_e32 v92, 16, v124
	v_pk_mul_f32 v[82:83], v[82:83], v[84:85]
	s_and_b64 vcc, exec, s[18:19]
	v_pk_mul_f32 v[78:79], v[78:79], v[82:83]
	v_pk_fma_f32 v[82:83], v[94:95], v[96:97], 1.0 op_sel_hi:[1,1,0] neg_lo:[1,0,0] neg_hi:[1,0,0]
	v_cvt_pk_bf16_f32 v78, v78, v79
	v_pk_fma_f32 v[82:83], v[96:97], v[82:83], v[96:97]
	v_readlane_b32 s81, v244, 15
	v_pk_mul_f32 v[82:83], v[90:91], v[82:83]
	v_readlane_b32 s82, v244, 16
	v_pk_mul_f32 v[80:81], v[80:81], v[82:83]
	v_pk_fma_f32 v[82:83], v[38:39], v[86:87], v[50:51]
	v_pk_fma_f32 v[86:87], v[40:41], v[88:89], v[52:53]
	v_pk_fma_f32 v[82:83], v[42:43], v[98:99], v[82:83]
	v_pk_fma_f32 v[86:87], v[44:45], v[100:101], v[86:87]
	v_pk_fma_f32 v[82:83], v[34:35], v[46:47], v[82:83]
	v_pk_fma_f32 v[86:87], v[36:37], v[48:49], v[86:87]
	v_mul_f32_e32 v79, 0x3d372713, v82
	v_mul_f32_e32 v79, v82, v79
	v_fma_f32 v79, v82, v79, v82
	v_mul_f32_e32 v79, 0xbfcc422a, v79
	v_min_f32_e32 v79, 0x42a00000, v79
	v_mul_f32_e32 v79, 0x3fb8aa3b, v79
	v_exp_f32_e32 v84, v79
	v_mul_f32_e32 v79, 0x3d372713, v83
	v_mul_f32_e32 v79, v83, v79
	v_fma_f32 v79, v83, v79, v83
	v_mul_f32_e32 v79, 0xbfcc422a, v79
	v_min_f32_e32 v79, 0x42a00000, v79
	v_mul_f32_e32 v79, 0x3fb8aa3b, v79
	v_exp_f32_e32 v85, v79
	v_mul_f32_e32 v79, 0x3d372713, v86
	v_mul_f32_e32 v79, v86, v79
	v_fma_f32 v79, v86, v79, v86
	v_mul_f32_e32 v79, 0xbfcc422a, v79
	v_min_f32_e32 v79, 0x42a00000, v79
	v_mul_f32_e32 v79, 0x3fb8aa3b, v79
	v_exp_f32_e32 v90, v79
	v_mul_f32_e32 v79, 0x3d372713, v87
	v_mul_f32_e32 v79, v87, v79
	v_fma_f32 v79, v87, v79, v87
	v_mul_f32_e32 v79, 0xbfcc422a, v79
	v_min_f32_e32 v79, 0x42a00000, v79
	v_pk_add_f32 v[84:85], v[84:85], 1.0 op_sel_hi:[1,0]
	v_mul_f32_e32 v79, 0x3fb8aa3b, v79
	v_rcp_f32_e32 v88, v84
	v_rcp_f32_e32 v89, v85
	v_exp_f32_e32 v91, v79
	v_cvt_pk_bf16_f32 v79, v80, v81
	v_readlane_b32 s83, v244, 17
	v_pk_fma_f32 v[80:81], v[84:85], v[88:89], 1.0 op_sel_hi:[1,1,0] neg_lo:[1,0,0] neg_hi:[1,0,0]
	v_pk_add_f32 v[84:85], v[90:91], 1.0 op_sel_hi:[1,0]
	v_pk_fma_f32 v[80:81], v[88:89], v[80:81], v[88:89]
	v_rcp_f32_e32 v90, v84
	v_rcp_f32_e32 v91, v85
	v_pk_mul_f32 v[80:81], v[82:83], v[80:81]
	v_readlane_b32 s84, v244, 18
	v_pk_mul_f32 v[74:75], v[74:75], v[80:81]
	v_pk_fma_f32 v[80:81], v[84:85], v[90:91], 1.0 op_sel_hi:[1,1,0] neg_lo:[1,0,0] neg_hi:[1,0,0]
	v_readlane_b32 s85, v244, 19
	v_pk_fma_f32 v[80:81], v[90:91], v[80:81], v[90:91]
	v_readlane_b32 s86, v244, 20
	v_pk_mul_f32 v[80:81], v[86:87], v[80:81]
	v_readlane_b32 s87, v244, 21
	v_pk_mul_f32 v[76:77], v[76:77], v[80:81]
	v_cvt_pk_bf16_f32 v80, v74, v75
	v_cvt_pk_bf16_f32 v81, v76, v77
	v_mad_i64_i32 v[74:75], s[56:57], v92, s79, v[178:179]
	global_store_dwordx4 v[74:75], v[78:81], off sc1
	v_add_u32_e32 v74, 0xffffc020, v124
	v_ashrrev_i32_e32 v74, 2, v74
	v_ashrrev_i32_e32 v75, 31, v74
	v_mad_i64_i32 v[76:77], s[56:57], v74, s77, 0
	v_lshl_add_u64 v[74:75], v[74:75], 1, v[202:203]
	v_mad_u64_u32 v[90:91], s[56:57], v74, s78, 0
	v_lshl_add_u64 v[88:89], s[92:93], 0, v[76:77]
	v_mad_i32_i24 v91, v75, s78, v91
	s_mov_b64 s[56:57], -1
	v_lshl_add_u64 v[86:87], v[214:215], 2, v[88:89]
	v_readlane_b32 s88, v244, 22
	v_readlane_b32 s89, v244, 23
	v_readlane_b32 s90, v244, 24
	v_readlane_b32 s91, v244, 25
	v_readlane_b32 s94, v244, 28
	v_readlane_b32 s95, v244, 29
	s_cbranch_vccnz .LBB0_1070
	v_add_co_u32_e32 v78, vcc, 0x2000, v86
	v_mov_b32_e32 v92, 0
	s_nop 0
	v_addc_co_u32_e32 v79, vcc, 0, v87, vcc
	global_load_dwordx4 v[74:77], v[86:87], off
	s_nop 0
	global_load_dwordx4 v[78:81], v[78:79], off offset:3072
	v_mov_b32_e32 v93, 0
	v_mov_b32_e32 v94, 0
	v_mov_b32_e32 v95, 0
	v_mov_b32_e32 v82, 0
	v_mov_b32_e32 v83, 0
	v_mov_b32_e32 v84, 0
	v_mov_b32_e32 v85, 0
	v_mov_b32_dpp v92, v22 row_ror:1 row_mask:0xf bank_mask:0xf
	v_mov_b32_dpp v93, v23 row_ror:1 row_mask:0xf bank_mask:0xf
	v_mov_b32_dpp v94, v24 row_ror:1 row_mask:0xf bank_mask:0xf
	v_mov_b32_dpp v95, v25 row_ror:1 row_mask:0xf bank_mask:0xf
	v_mov_b32_dpp v82, v22 row_ror:2 row_mask:0xf bank_mask:0xf
	v_mov_b32_dpp v83, v23 row_ror:2 row_mask:0xf bank_mask:0xf
	v_mov_b32_dpp v84, v24 row_ror:2 row_mask:0xf bank_mask:0xf
	v_mov_b32_dpp v85, v25 row_ror:2 row_mask:0xf bank_mask:0xf
	s_waitcnt vmcnt(0)
	v_cndmask_b32_e64 v77, v77, v81, s[10:11]
	v_cndmask_b32_e64 v76, v76, v80, s[10:11]
	v_cndmask_b32_e64 v75, v75, v79, s[10:11]
	v_cndmask_b32_e64 v74, v74, v78, s[10:11]
	s_and_saveexec_b64 s[56:57], s[8:9]
	s_cbranch_execz .LBB0_1069
	v_lshl_add_u64 v[74:75], s[42:43], 0, v[90:91]
	v_lshl_add_u64 v[74:75], v[214:215], 2, v[74:75]
	global_store_dwordx4 v[74:75], v[22:25], off sc1
	v_mov_b64_e32 v[74:75], v[82:83]
	v_mov_b64_e32 v[76:77], v[84:85]

; __device__ __forceinline__ f32x4 ror1v(f32x4 v) { return f32x4{dpp_ror1(v.x), dpp_ror1(v.y), dpp_ror1(v.z), dpp_ror1(v.w)}; }
; __device__ __forceinline__ f32x4 ror2v(f32x4 v) { return f32x4{dpp_ror2(v.x), dpp_ror2(v.y), dpp_ror2(v.z), dpp_ror2(v.w)}; }
; template <int EPI>
; __device__ __forceinline__ void epilogue(const Params& p, f32x4 (&acc)[2][2][4][2], const int pm, const int pn, const int wr, const int wc, const int fr, const int fq) {
;     ...
;             const int sidx = row - MP, b = sidx >> 2, tt = sidx & 3;
;             const f32x4 st0 = *(const f32x4*)(p.in[6] + ((size_t)b * 2 + 0) * DFF + j0);
;             const f32x4 st1 = *(const f32x4*)(p.in[6] + ((size_t)b * 2 + 1) * DFF + j0);
;             const f32x4 s1 = ror1v(a0), s2 = ror2v(a0);
;             am1 = (tt >= 1) ? s1 : st1;
;             am2 = (tt >= 2) ? s2 : ((tt == 1) ? st1 : st0);
;             if (tt >= 2) *(f32x4*)(p.out + O_CS + ((size_t)b * 2 + (tt - 2)) * DFF + j0) = a0;
.LBB0_1072:
	s_and_b64 vcc, exec, s[18:19]
	s_mov_b64 s[56:57], -1
	s_cbranch_vccnz .LBB0_1076
	v_lshl_add_u64 v[62:63], v[216:217], 2, v[88:89]
	v_add_co_u32_e32 v82, vcc, 0x2000, v62
	v_mov_b32_e32 v92, 0
	s_nop 0
	v_addc_co_u32_e32 v83, vcc, 0, v63, vcc
	global_load_dwordx4 v[62:65], v[86:87], off offset:16
	s_nop 0
	global_load_dwordx4 v[82:85], v[82:83], off offset:3072
	v_mov_b32_e32 v93, 0
	v_mov_b32_e32 v94, 0
	v_mov_b32_e32 v95, 0
	v_mov_b32_e32 v86, 0
	v_mov_b32_e32 v87, 0
	v_mov_b32_e32 v88, 0
	v_mov_b32_e32 v89, 0
	v_mov_b32_dpp v92, v18 row_ror:1 row_mask:0xf bank_mask:0xf
	v_mov_b32_dpp v93, v19 row_ror:1 row_mask:0xf bank_mask:0xf
	v_mov_b32_dpp v94, v20 row_ror:1 row_mask:0xf bank_mask:0xf
	v_mov_b32_dpp v95, v21 row_ror:1 row_mask:0xf bank_mask:0xf
	v_mov_b32_dpp v86, v18 row_ror:2 row_mask:0xf bank_mask:0xf
	v_mov_b32_dpp v87, v19 row_ror:2 row_mask:0xf bank_mask:0xf
	v_mov_b32_dpp v88, v20 row_ror:2 row_mask:0xf bank_mask:0xf
	v_mov_b32_dpp v89, v21 row_ror:2 row_mask:0xf bank_mask:0xf
	s_waitcnt vmcnt(0)
	v_cndmask_b32_e64 v65, v65, v85, s[10:11]
	v_cndmask_b32_e64 v64, v64, v84, s[10:11]
	v_cndmask_b32_e64 v63, v63, v83, s[10:11]
	v_cndmask_b32_e64 v62, v62, v82, s[10:11]
	s_and_saveexec_b64 s[56:57], s[8:9]
	s_cbranch_execz .LBB0_1075
	v_lshl_add_u64 v[62:63], s[42:43], 0, v[90:91]
	v_lshl_add_u64 v[62:63], v[214:215], 2, v[62:63]
	global_store_dwordx4 v[62:63], v[18:21], off offset:16 sc1
	v_mov_b64_e32 v[62:63], v[86:87]
	v_mov_b64_e32 v[64:65], v[88:89]

; __device__ __forceinline__ float gelu_tanh(float x) { float z = 1.5957691216057308f * (x + 0.044715f * x * x * x); return x * rcp_nr(1.f + __expf(fminf(-z, 80.f))); }
; __device__ __forceinline__ u32x2 pk4(f32x4 v) { u32x2 r; r.x = pk2(v.x, v.y); r.y = pk2(v.z, v.w); return r; }
; __device__ __forceinline__ f32x4 shr1v(f32x4 o, f32x4 v) { return f32x4{dpp_shr1_old(o.x, v.x), dpp_shr1_old(o.y, v.y), dpp_shr1_old(o.z, v.z), dpp_shr1_old(o.w, v.w)}; }
; __device__ __forceinline__ f32x4 shr2v(f32x4 o, f32x4 v) { return f32x4{dpp_shr2_old(o.x, v.x), dpp_shr2_old(o.y, v.y), dpp_shr2_old(o.z, v.z), dpp_shr2_old(o.w, v.w)}; }
; __device__ __forceinline__ f32x4 ror1v(f32x4 v) { return f32x4{dpp_ror1(v.x), dpp_ror1(v.y), dpp_ror1(v.z), dpp_ror1(v.w)}; }
; template <int EPI>
; __device__ __forceinline__ void epilogue(const Params& p, f32x4 (&acc)[2][2][4][2], const int pm, const int pn, const int wr, const int wc, const int fr, const int fq) {
;     ...
;           if (prompt) {
;             f32x4 o1 = f32x4{0.f, 0.f, 0.f, 0.f}, o2 = o1;
;             if (m > 0) { o1 = ror1v(acc[ai][bj][m > 0 ? m - 1 : 0][0]); o2 = ror2v(acc[ai][bj][m > 0 ? m - 1 : 0][0]); }
;             am1 = shr1v(o1, a0); am2 = shr2v(o2, a0);
;             if (m == 0 && fr < 2 && (row & 2047) >= 2) defer = true;
;             if (m == 3 && fr >= 14) *(f32x4*)(HA1 + ((size_t)(rblk >> 6) * 2 + (fr - 14)) * DFF + j0) = a0;
;             const int pos = row & 2047;
;             if (pos >= 2046) *(f32x4*)(p.out + O_CP + ((size_t)(row >> 11) * 2 + (pos - 2046)) * DFF + j0) = a0;
;     ...
;           f32x4 h;
;           h.x = gelu_tanh(cb[bj].x + w0[bj].x * am2.x + w1[bj].x * am1.x + w2[bj].x * a0.x) * g.x;
;           h.y = gelu_tanh(cb[bj].y + w0[bj].y * am2.y + w1[bj].y * am1.y + w2[bj].y * a0.y) * g.y;
;           h.z = gelu_tanh(cb[bj].z + w0[bj].z * am2.z + w1[bj].z * am1.z + w2[bj].z * a0.z) * g.z;
;           h.w = gelu_tanh(cb[bj].w + w0[bj].w * am2.w + w1[bj].w * am1.w + w2[bj].w * a0.w) * g.w;
;           ho[bj] = pk4(h);
;           if (defer) {
;             *(f32x4*)(HA0 + ((size_t)(rblk >> 6) * 2 + fr) * DFF + j0) = a0;
;             *(f32x4*)(HG0 + ((size_t)(rblk >> 6) * 2 + fr) * DFF + j0) = g;
;           }
;         }
;         if (!defer) *(u32x4*)(H + (size_t)row * DFF + jb) = u32x4{ho[0].x, ho[0].y, ho[1].x, ho[1].y};
.LBB0_1078:
	v_pk_fma_f32 v[34:35], v[54:55], v[74:75], v[70:71]
	v_pk_fma_f32 v[74:75], v[56:57], v[76:77], v[72:73]
	v_pk_fma_f32 v[34:35], v[58:59], v[78:79], v[34:35]
	v_pk_fma_f32 v[74:75], v[60:61], v[80:81], v[74:75]
	v_pk_fma_f32 v[34:35], v[22:23], v[66:67], v[34:35]
	v_pk_fma_f32 v[74:75], v[24:25], v[68:69], v[74:75]
	v_mul_f32_e32 v36, 0x3d372713, v34
	v_mul_f32_e32 v37, 0x3d372713, v35
	v_mul_f32_e32 v36, v34, v36
	v_mul_f32_e32 v37, v35, v37
	v_fma_f32 v36, v34, v36, v34
	v_fma_f32 v37, v35, v37, v35
	v_mul_f32_e32 v36, 0xbfcc422a, v36
	v_mul_f32_e32 v37, 0xbfcc422a, v37
	v_mul_f32_e32 v78, 0x3d372713, v74
	v_mul_f32_e32 v79, 0x3d372713, v75
	v_min_f32_e32 v36, 0x42a00000, v36
	v_min_f32_e32 v37, 0x42a00000, v37
	v_mul_f32_e32 v78, v74, v78
	v_mul_f32_e32 v79, v75, v79
	v_mul_f32_e32 v36, 0x3fb8aa3b, v36
	v_mul_f32_e32 v37, 0x3fb8aa3b, v37
	v_fma_f32 v78, v74, v78, v74
	v_fma_f32 v79, v75, v79, v75
	v_exp_f32_e32 v36, v36
	v_exp_f32_e32 v37, v37
	v_mul_f32_e32 v78, 0xbfcc422a, v78
	v_mul_f32_e32 v79, 0xbfcc422a, v79
	v_min_f32_e32 v78, 0x42a00000, v78
	v_min_f32_e32 v79, 0x42a00000, v79
	v_mul_f32_e32 v78, 0x3fb8aa3b, v78
	v_mul_f32_e32 v79, 0x3fb8aa3b, v79
	v_exp_f32_e32 v78, v78
	v_exp_f32_e32 v79, v79
	v_pk_add_f32 v[36:37], v[36:37], 1.0 op_sel_hi:[1,0]
	v_readlane_b32 s80, v244, 14
	v_rcp_f32_e32 v76, v36
	v_rcp_f32_e32 v77, v37
	v_pk_add_f32 v[78:79], v[78:79], 1.0 op_sel_hi:[1,0]
	v_readlane_b32 s92, v244, 26
	v_rcp_f32_e32 v80, v78
	v_rcp_f32_e32 v81, v79
	v_pk_fma_f32 v[36:37], v[36:37], v[76:77], 1.0 op_sel_hi:[1,1,0] neg_lo:[1,0,0] neg_hi:[1,0,0]
	v_readlane_b32 s93, v244, 27
	v_pk_fma_f32 v[36:37], v[76:77], v[36:37], v[76:77]
	v_or_b32_e32 v76, 32, v124
	v_pk_mul_f32 v[34:35], v[34:35], v[36:37]
	s_and_b64 vcc, exec, s[18:19]
	v_pk_mul_f32 v[30:31], v[30:31], v[34:35]
	v_pk_fma_f32 v[34:35], v[78:79], v[80:81], 1.0 op_sel_hi:[1,1,0] neg_lo:[1,0,0] neg_hi:[1,0,0]
	v_cvt_pk_bf16_f32 v30, v30, v31
	v_pk_fma_f32 v[34:35], v[80:81], v[34:35], v[80:81]
	v_bitop3_b32 v80, v124, s0, 48 bitop3:0xc8
	v_pk_mul_f32 v[34:35], v[74:75], v[34:35]
	v_readlane_b32 s81, v244, 15
	v_pk_mul_f32 v[32:33], v[32:33], v[34:35]
	v_pk_fma_f32 v[34:35], v[38:39], v[62:63], v[50:51]
	v_pk_fma_f32 v[62:63], v[40:41], v[64:65], v[52:53]
	v_pk_fma_f32 v[34:35], v[42:43], v[82:83], v[34:35]
	v_pk_fma_f32 v[62:63], v[44:45], v[84:85], v[62:63]
	v_pk_fma_f32 v[34:35], v[18:19], v[46:47], v[34:35]
	v_pk_fma_f32 v[62:63], v[20:21], v[48:49], v[62:63]
	v_mul_f32_e32 v31, 0x3d372713, v34
	v_mul_f32_e32 v31, v34, v31
	v_fma_f32 v31, v34, v31, v34
	v_mul_f32_e32 v31, 0xbfcc422a, v31
	v_min_f32_e32 v31, 0x42a00000, v31
	v_mul_f32_e32 v31, 0x3fb8aa3b, v31
	v_exp_f32_e32 v36, v31
	v_mul_f32_e32 v31, 0x3d372713, v35
	v_mul_f32_e32 v31, v35, v31
	v_fma_f32 v31, v35, v31, v35
	v_mul_f32_e32 v31, 0xbfcc422a, v31
	v_min_f32_e32 v31, 0x42a00000, v31
	v_mul_f32_e32 v31, 0x3fb8aa3b, v31
	v_exp_f32_e32 v37, v31
	v_mul_f32_e32 v31, 0x3d372713, v62
	v_mul_f32_e32 v31, v62, v31
	v_fma_f32 v31, v62, v31, v62
	v_mul_f32_e32 v31, 0xbfcc422a, v31
	v_min_f32_e32 v31, 0x42a00000, v31
	v_mul_f32_e32 v31, 0x3fb8aa3b, v31
	v_exp_f32_e32 v74, v31
	v_mul_f32_e32 v31, 0x3d372713, v63
	v_mul_f32_e32 v31, v63, v31
	v_fma_f32 v31, v63, v31, v63
	v_mul_f32_e32 v31, 0xbfcc422a, v31
	v_min_f32_e32 v31, 0x42a00000, v31
	v_pk_add_f32 v[36:37], v[36:37], 1.0 op_sel_hi:[1,0]
	v_mul_f32_e32 v31, 0x3fb8aa3b, v31
	v_rcp_f32_e32 v64, v36
	v_rcp_f32_e32 v65, v37
	v_exp_f32_e32 v75, v31
	v_cvt_pk_bf16_f32 v31, v32, v33
	v_readlane_b32 s82, v244, 16
	v_pk_fma_f32 v[32:33], v[36:37], v[64:65], 1.0 op_sel_hi:[1,1,0] neg_lo:[1,0,0] neg_hi:[1,0,0]
	v_pk_add_f32 v[36:37], v[74:75], 1.0 op_sel_hi:[1,0]
	v_pk_fma_f32 v[32:33], v[64:65], v[32:33], v[64:65]
	v_rcp_f32_e32 v74, v36
	v_rcp_f32_e32 v75, v37
	v_pk_mul_f32 v[32:33], v[34:35], v[32:33]
	v_readlane_b32 s83, v244, 17
	v_pk_mul_f32 v[26:27], v[26:27], v[32:33]
	v_pk_fma_f32 v[32:33], v[36:37], v[74:75], 1.0 op_sel_hi:[1,1,0] neg_lo:[1,0,0] neg_hi:[1,0,0]
	v_readlane_b32 s84, v244, 18
	v_pk_fma_f32 v[32:33], v[74:75], v[32:33], v[74:75]
	v_readlane_b32 s85, v244, 19
	v_pk_mul_f32 v[32:33], v[62:63], v[32:33]
	v_readlane_b32 s86, v244, 20
	v_pk_mul_f32 v[28:29], v[28:29], v[32:33]
	v_cvt_pk_bf16_f32 v32, v26, v27
	v_cvt_pk_bf16_f32 v33, v28, v29
	v_mad_i64_i32 v[26:27], s[56:57], v76, s79, v[178:179]
	global_store_dwordx4 v[26:27], v[30:33], off sc1
	v_add_u32_e32 v26, 0xffffc030, v124
	v_ashrrev_i32_e32 v76, 2, v26
	v_mad_i64_i32 v[26:27], s[56:57], v76, s77, 0
	v_lshl_add_u64 v[64:65], s[92:93], 0, v[26:27]
	v_cmp_lt_u32_e64 s[56:57], s1, v80
	v_lshl_add_u64 v[62:63], v[214:215], 2, v[64:65]
	v_readlane_b32 s87, v244, 21
	v_readlane_b32 s88, v244, 22
	v_readlane_b32 s89, v244, 23
	v_readlane_b32 s90, v244, 24
	v_readlane_b32 s91, v244, 25
	v_readlane_b32 s94, v244, 28
	v_readlane_b32 s95, v244, 29
	s_cbranch_vccnz .LBB0_1082
	v_add_co_u32_e32 v30, vcc, 0x2000, v62
	v_mov_b32_e32 v74, 0
	s_nop 0
	v_addc_co_u32_e32 v31, vcc, 0, v63, vcc
	global_load_dwordx4 v[26:29], v[62:63], off
	s_nop 0
	global_load_dwordx4 v[30:33], v[30:31], off offset:3072
	v_mov_b32_e32 v75, 0
	v_mov_b32_e32 v77, 0
	v_mov_b32_e32 v78, 0
	v_mov_b32_e32 v34, 0
	v_mov_b32_e32 v35, 0
	v_mov_b32_e32 v36, 0
	v_mov_b32_e32 v37, 0
	s_mov_b64 s[60:61], 0
	v_mov_b32_dpp v74, v14 row_ror:1 row_mask:0xf bank_mask:0xf
	v_mov_b32_dpp v75, v15 row_ror:1 row_mask:0xf bank_mask:0xf
	v_mov_b32_dpp v77, v16 row_ror:1 row_mask:0xf bank_mask:0xf
	v_mov_b32_dpp v78, v17 row_ror:1 row_mask:0xf bank_mask:0xf
	v_mov_b32_dpp v34, v14 row_ror:2 row_mask:0xf bank_mask:0xf
	v_mov_b32_dpp v35, v15 row_ror:2 row_mask:0xf bank_mask:0xf
	v_mov_b32_dpp v36, v16 row_ror:2 row_mask:0xf bank_mask:0xf
	v_mov_b32_dpp v37, v17 row_ror:2 row_mask:0xf bank_mask:0xf
	s_mov_b64 s[58:59], 0
	s_waitcnt vmcnt(0)
	v_cndmask_b32_e64 v29, v29, v33, s[10:11]
	v_cndmask_b32_e64 v28, v28, v32, s[10:11]
	v_cndmask_b32_e64 v27, v27, v31, s[10:11]
	v_cndmask_b32_e64 v26, v26, v30, s[10:11]
	s_and_saveexec_b64 s[62:63], s[8:9]
	v_mov_b64_e32 v[26:27], v[34:35]
	s_mov_b64 s[58:59], exec
	v_mov_b64_e32 v[28:29], v[36:37]
	s_or_b64 exec, exec, s[62:63]
	v_cndmask_b32_e64 v33, v78, v33, s[6:7]
	v_cndmask_b32_e64 v32, v77, v32, s[6:7]
	v_cndmask_b32_e64 v31, v75, v31, s[6:7]
	v_cndmask_b32_e64 v30, v74, v30, s[6:7]
	s_branch .LBB0_1083

; __device__ __forceinline__ f32x4 shr1v(f32x4 o, f32x4 v) { return f32x4{dpp_shr1_old(o.x, v.x), dpp_shr1_old(o.y, v.y), dpp_shr1_old(o.z, v.z), dpp_shr1_old(o.w, v.w)}; }
; __device__ __forceinline__ f32x4 shr2v(f32x4 o, f32x4 v) { return f32x4{dpp_shr2_old(o.x, v.x), dpp_shr2_old(o.y, v.y), dpp_shr2_old(o.z, v.z), dpp_shr2_old(o.w, v.w)}; }
; __device__ __forceinline__ f32x4 ror1v(f32x4 v) { return f32x4{dpp_ror1(v.x), dpp_ror1(v.y), dpp_ror1(v.z), dpp_ror1(v.w)}; }
; __device__ __forceinline__ f32x4 ror2v(f32x4 v) { return f32x4{dpp_ror2(v.x), dpp_ror2(v.y), dpp_ror2(v.z), dpp_ror2(v.w)}; }
; template <int EPI>
; __device__ __forceinline__ void epilogue(const Params& p, f32x4 (&acc)[2][2][4][2], const int pm, const int pn, const int wr, const int wc, const int fr, const int fq) {
;     ...
;           if (prompt) {
;             f32x4 o1 = f32x4{0.f, 0.f, 0.f, 0.f}, o2 = o1;
;             if (m > 0) { o1 = ror1v(acc[ai][bj][m > 0 ? m - 1 : 0][0]); o2 = ror2v(acc[ai][bj][m > 0 ? m - 1 : 0][0]); }
;             am1 = shr1v(o1, a0); am2 = shr2v(o2, a0);
;             if (m == 0 && fr < 2 && (row & 2047) >= 2) defer = true;
;             if (m == 3 && fr >= 14) *(f32x4*)(HA1 + ((size_t)(rblk >> 6) * 2 + (fr - 14)) * DFF + j0) = a0;
;             const int pos = row & 2047;
;             if (pos >= 2046) *(f32x4*)(p.out + O_CP + ((size_t)(row >> 11) * 2 + (pos - 2046)) * DFF + j0) = a0;
.LBB0_1083:
	v_lshl_add_u64 v[34:35], s[54:55], 0, v[204:205]
	v_mov_b64_e32 v[36:37], s[34:35]
	v_mad_u64_u32 v[74:75], s[54:55], v34, s78, v[36:37]
	v_ashrrev_i32_e32 v77, 31, v76
	v_mad_i32_i24 v75, v35, s78, v75
	s_ashr_i32 s54, s47, 11
	v_lshl_add_u64 v[34:35], v[76:77], 1, v[202:203]
	s_ashr_i32 s55, s54, 31
	v_mad_u64_u32 v[78:79], s[62:63], v34, s78, 0
	v_add_u32_e32 v198, 0xfffff802, v80
	v_mad_i32_i24 v79, v35, s78, v79
	v_lshl_add_u64 v[34:35], s[54:55], 1, v[198:199]
	v_mad_u64_u32 v[76:77], s[54:55], v34, s78, 0
	v_mad_i32_i24 v77, v35, s78, v77
	s_and_b64 vcc, exec, s[60:61]
	s_cbranch_vccz .LBB0_1087
	v_mov_b32_e32 v30, v199
	v_mov_b32_e32 v31, v199
	v_mov_b32_e32 v32, v199
	v_mov_b32_e32 v33, v199
	v_mov_b32_e32 v26, v199
	v_mov_b32_e32 v27, v199
	v_mov_b32_e32 v28, v199
	v_mov_b32_e32 v29, v199
	v_mov_b32_dpp v30, v22 row_ror:1 row_mask:0xf bank_mask:0xf
	v_mov_b32_dpp v31, v23 row_ror:1 row_mask:0xf bank_mask:0xf
	v_mov_b32_dpp v32, v24 row_ror:1 row_mask:0xf bank_mask:0xf
	v_mov_b32_dpp v33, v25 row_ror:1 row_mask:0xf bank_mask:0xf
	v_mov_b32_dpp v26, v22 row_ror:2 row_mask:0xf bank_mask:0xf
	v_mov_b32_dpp v27, v23 row_ror:2 row_mask:0xf bank_mask:0xf
	v_mov_b32_dpp v28, v24 row_ror:2 row_mask:0xf bank_mask:0xf
	v_mov_b32_dpp v29, v25 row_ror:2 row_mask:0xf bank_mask:0xf
	v_mov_b32_dpp v30, v14 row_shr:1 row_mask:0xf bank_mask:0xf
	v_mov_b32_dpp v31, v15 row_shr:1 row_mask:0xf bank_mask:0xf
	v_mov_b32_dpp v32, v16 row_shr:1 row_mask:0xf bank_mask:0xf
	v_mov_b32_dpp v33, v17 row_shr:1 row_mask:0xf bank_mask:0xf
	v_mov_b32_dpp v26, v14 row_shr:2 row_mask:0xf bank_mask:0xf
	v_mov_b32_dpp v27, v15 row_shr:2 row_mask:0xf bank_mask:0xf
	v_mov_b32_dpp v28, v16 row_shr:2 row_mask:0xf bank_mask:0xf
	v_mov_b32_dpp v29, v17 row_shr:2 row_mask:0xf bank_mask:0xf
	s_and_saveexec_b64 s[54:55], s[14:15]
	s_cbranch_execz .LBB0_1086
	v_lshl_add_u64 v[22:23], v[214:215], 2, v[74:75]
	global_store_dwordx4 v[22:23], v[14:17], off sc1

; __device__ __forceinline__ f32x4 ror1v(f32x4 v) { return f32x4{dpp_ror1(v.x), dpp_ror1(v.y), dpp_ror1(v.z), dpp_ror1(v.w)}; }
; __device__ __forceinline__ f32x4 ror2v(f32x4 v) { return f32x4{dpp_ror2(v.x), dpp_ror2(v.y), dpp_ror2(v.z), dpp_ror2(v.w)}; }
; template <int EPI>
; __device__ __forceinline__ void epilogue(const Params& p, f32x4 (&acc)[2][2][4][2], const int pm, const int pn, const int wr, const int wc, const int fr, const int fq) {
;     ...
;             if (m == 3 && fr >= 14) *(f32x4*)(HA1 + ((size_t)(rblk >> 6) * 2 + (fr - 14)) * DFF + j0) = a0;
;             const int pos = row & 2047;
;             if (pos >= 2046) *(f32x4*)(p.out + O_CP + ((size_t)(row >> 11) * 2 + (pos - 2046)) * DFF + j0) = a0;
;           } else {
;             const int sidx = row - MP, b = sidx >> 2, tt = sidx & 3;
;             const f32x4 st0 = *(const f32x4*)(p.in[6] + ((size_t)b * 2 + 0) * DFF + j0);
;             const f32x4 st1 = *(const f32x4*)(p.in[6] + ((size_t)b * 2 + 1) * DFF + j0);
;             const f32x4 s1 = ror1v(a0), s2 = ror2v(a0);
;             am1 = (tt >= 1) ? s1 : st1;
;             am2 = (tt >= 2) ? s2 : ((tt == 1) ? st1 : st0);
;             if (tt >= 2) *(f32x4*)(p.out + O_CS + ((size_t)b * 2 + (tt - 2)) * DFF + j0) = a0;
.LBB0_1088:
	v_readlane_b32 s84, v244, 0
	v_readlane_b32 s85, v244, 1
	s_add_u32 s54, s84, s54
	s_addc_u32 s55, s85, s55
	v_lshl_add_u64 v[22:23], s[54:55], 0, v[22:23]
	v_lshl_add_u64 v[22:23], v[214:215], 2, v[22:23]
	v_readlane_b32 s86, v244, 2
	v_readlane_b32 s87, v244, 3
	global_store_dwordx4 v[22:23], v[14:17], off sc1
.LBB0_1089:
	s_or_b64 exec, exec, s[60:61]
	s_and_b64 vcc, exec, s[18:19]
	s_mov_b64 s[18:19], -1
	s_cbranch_vccnz .LBB0_1093
	v_lshl_add_u64 v[22:23], v[216:217], 2, v[64:65]
	v_add_co_u32_e32 v34, vcc, 0x2000, v22
	v_mov_b32_e32 v80, 0
	s_nop 0
	v_addc_co_u32_e32 v35, vcc, 0, v23, vcc
	global_load_dwordx4 v[22:25], v[62:63], off offset:16
	s_nop 0
	global_load_dwordx4 v[34:37], v[34:35], off offset:3072
	v_mov_b32_e32 v81, 0
	v_mov_b32_e32 v82, 0
	v_mov_b32_e32 v83, 0
	v_mov_b32_e32 v62, 0
	v_mov_b32_e32 v63, 0
	v_mov_b32_e32 v64, 0
	v_mov_b32_e32 v65, 0
	v_mov_b32_dpp v80, v6 row_ror:1 row_mask:0xf bank_mask:0xf
	v_mov_b32_dpp v81, v7 row_ror:1 row_mask:0xf bank_mask:0xf
	v_mov_b32_dpp v82, v8 row_ror:1 row_mask:0xf bank_mask:0xf
	v_mov_b32_dpp v83, v9 row_ror:1 row_mask:0xf bank_mask:0xf
	v_mov_b32_dpp v62, v6 row_ror:2 row_mask:0xf bank_mask:0xf
	v_mov_b32_dpp v63, v7 row_ror:2 row_mask:0xf bank_mask:0xf
	v_mov_b32_dpp v64, v8 row_ror:2 row_mask:0xf bank_mask:0xf
	v_mov_b32_dpp v65, v9 row_ror:2 row_mask:0xf bank_mask:0xf
	s_waitcnt vmcnt(0)
	v_cndmask_b32_e64 v25, v25, v37, s[10:11]
	v_cndmask_b32_e64 v24, v24, v36, s[10:11]
	v_cndmask_b32_e64 v23, v23, v35, s[10:11]
	v_cndmask_b32_e64 v22, v22, v34, s[10:11]
	s_and_saveexec_b64 s[18:19], s[8:9]
	s_cbranch_execz .LBB0_1092
	v_lshl_add_u64 v[22:23], s[42:43], 0, v[78:79]
	v_lshl_add_u64 v[22:23], v[214:215], 2, v[22:23]
	global_store_dwordx4 v[22:23], v[6:9], off offset:16 sc1
	v_mov_b64_e32 v[22:23], v[62:63]
	v_mov_b64_e32 v[24:25], v[64:65]

; __device__ __forceinline__ f32x4 shr1v(f32x4 o, f32x4 v) { return f32x4{dpp_shr1_old(o.x, v.x), dpp_shr1_old(o.y, v.y), dpp_shr1_old(o.z, v.z), dpp_shr1_old(o.w, v.w)}; }
; __device__ __forceinline__ f32x4 shr2v(f32x4 o, f32x4 v) { return f32x4{dpp_shr2_old(o.x, v.x), dpp_shr2_old(o.y, v.y), dpp_shr2_old(o.z, v.z), dpp_shr2_old(o.w, v.w)}; }
; __device__ __forceinline__ f32x4 ror1v(f32x4 v) { return f32x4{dpp_ror1(v.x), dpp_ror1(v.y), dpp_ror1(v.z), dpp_ror1(v.w)}; }
; __device__ __forceinline__ f32x4 ror2v(f32x4 v) { return f32x4{dpp_ror2(v.x), dpp_ror2(v.y), dpp_ror2(v.z), dpp_ror2(v.w)}; }
; template <int EPI>
; __device__ __forceinline__ void epilogue(const Params& p, f32x4 (&acc)[2][2][4][2], const int pm, const int pn, const int wr, const int wc, const int fr, const int fq) {
;     ...
;           if (prompt) {
;             f32x4 o1 = f32x4{0.f, 0.f, 0.f, 0.f}, o2 = o1;
;             if (m > 0) { o1 = ror1v(acc[ai][bj][m > 0 ? m - 1 : 0][0]); o2 = ror2v(acc[ai][bj][m > 0 ? m - 1 : 0][0]); }
;             am1 = shr1v(o1, a0); am2 = shr2v(o2, a0);
;             if (m == 0 && fr < 2 && (row & 2047) >= 2) defer = true;
;             if (m == 3 && fr >= 14) *(f32x4*)(HA1 + ((size_t)(rblk >> 6) * 2 + (fr - 14)) * DFF + j0) = a0;
;             const int pos = row & 2047;
;             if (pos >= 2046) *(f32x4*)(p.out + O_CP + ((size_t)(row >> 11) * 2 + (pos - 2046)) * DFF + j0) = a0;
.LBB0_1094:
	v_mov_b32_e32 v34, v199
	v_mov_b32_e32 v35, v199
	v_mov_b32_e32 v36, v199
	v_mov_b32_e32 v37, v199
	v_mov_b32_e32 v22, v199
	v_mov_b32_e32 v23, v199
	v_mov_b32_e32 v24, v199
	v_mov_b32_e32 v25, v199
	v_mov_b32_dpp v34, v18 row_ror:1 row_mask:0xf bank_mask:0xf
	v_mov_b32_dpp v35, v19 row_ror:1 row_mask:0xf bank_mask:0xf
	v_mov_b32_dpp v36, v20 row_ror:1 row_mask:0xf bank_mask:0xf
	v_mov_b32_dpp v37, v21 row_ror:1 row_mask:0xf bank_mask:0xf
	v_mov_b32_dpp v22, v18 row_ror:2 row_mask:0xf bank_mask:0xf
	v_mov_b32_dpp v23, v19 row_ror:2 row_mask:0xf bank_mask:0xf
	v_mov_b32_dpp v24, v20 row_ror:2 row_mask:0xf bank_mask:0xf
	v_mov_b32_dpp v25, v21 row_ror:2 row_mask:0xf bank_mask:0xf
	v_mov_b32_dpp v34, v6 row_shr:1 row_mask:0xf bank_mask:0xf
	v_mov_b32_dpp v35, v7 row_shr:1 row_mask:0xf bank_mask:0xf
	v_mov_b32_dpp v36, v8 row_shr:1 row_mask:0xf bank_mask:0xf
	v_mov_b32_dpp v37, v9 row_shr:1 row_mask:0xf bank_mask:0xf
	v_mov_b32_dpp v22, v6 row_shr:2 row_mask:0xf bank_mask:0xf
	v_mov_b32_dpp v23, v7 row_shr:2 row_mask:0xf bank_mask:0xf
	v_mov_b32_dpp v24, v8 row_shr:2 row_mask:0xf bank_mask:0xf
	v_mov_b32_dpp v25, v9 row_shr:2 row_mask:0xf bank_mask:0xf
	s_and_saveexec_b64 s[18:19], s[14:15]
	s_cbranch_execz .LBB0_1096
	v_lshl_add_u64 v[18:19], v[214:215], 2, v[74:75]
	global_store_dwordx4 v[18:19], v[6:9], off offset:16 sc1
.LBB0_1096:
	s_or_b64 exec, exec, s[18:19]
	s_and_saveexec_b64 s[18:19], s[56:57]
	s_cbranch_execz .LBB0_1098
	v_lshl_add_u64 v[18:19], s[44:45], 0, v[76:77]
	v_lshl_add_u64 v[18:19], v[214:215], 2, v[18:19]
	global_store_dwordx4 v[18:19], v[6:9], off offset:16 sc1

; __device__ __forceinline__ float gelu_tanh(float x) { float z = 1.5957691216057308f * (x + 0.044715f * x * x * x); return x * rcp_nr(1.f + __expf(fminf(-z, 80.f))); }
; __device__ __forceinline__ u32x2 pk4(f32x4 v) { u32x2 r; r.x = pk2(v.x, v.y); r.y = pk2(v.z, v.w); return r; }
; template <int EPI>
; __device__ __forceinline__ void epilogue(const Params& p, f32x4 (&acc)[2][2][4][2], const int pm, const int pn, const int wr, const int wc, const int fr, const int fq) {
;     ...
;           f32x4 h;
;           h.x = gelu_tanh(cb[bj].x + w0[bj].x * am2.x + w1[bj].x * am1.x + w2[bj].x * a0.x) * g.x;
;           h.y = gelu_tanh(cb[bj].y + w0[bj].y * am2.y + w1[bj].y * am1.y + w2[bj].y * a0.y) * g.y;
;           h.z = gelu_tanh(cb[bj].z + w0[bj].z * am2.z + w1[bj].z * am1.z + w2[bj].z * a0.z) * g.z;
;           h.w = gelu_tanh(cb[bj].w + w0[bj].w * am2.w + w1[bj].w * am1.w + w2[bj].w * a0.w) * g.w;
;           ho[bj] = pk4(h);
;           if (defer) {
;             *(f32x4*)(HA0 + ((size_t)(rblk >> 6) * 2 + fr) * DFF + j0) = a0;
;             *(f32x4*)(HG0 + ((size_t)(rblk >> 6) * 2 + fr) * DFF + j0) = g;
;           }
;         }
;         if (!defer) *(u32x4*)(H + (size_t)row * DFF + jb) = u32x4{ho[0].x, ho[0].y, ho[1].x, ho[1].y};
;       }
.LBB0_1099:
	v_pk_fma_f32 v[20:21], v[54:55], v[26:27], v[70:71]
	v_pk_fma_f32 v[26:27], v[56:57], v[28:29], v[72:73]
	v_pk_fma_f32 v[20:21], v[58:59], v[30:31], v[20:21]
	v_pk_fma_f32 v[26:27], v[60:61], v[32:33], v[26:27]
	v_pk_fma_f32 v[14:15], v[14:15], v[66:67], v[20:21]
	v_pk_fma_f32 v[16:17], v[16:17], v[68:69], v[26:27]
	v_mul_f32_e32 v19, 0x3d372713, v14
	v_mul_f32_e32 v19, v14, v19
	v_fma_f32 v19, v14, v19, v14
	v_mul_f32_e32 v19, 0xbfcc422a, v19
	v_min_f32_e32 v19, 0x42a00000, v19
	v_mul_f32_e32 v19, 0x3fb8aa3b, v19
	v_exp_f32_e32 v20, v19
	v_mul_f32_e32 v19, 0x3d372713, v15
	v_mul_f32_e32 v19, v15, v19
	v_fma_f32 v19, v15, v19, v15
	v_mul_f32_e32 v19, 0xbfcc422a, v19
	v_min_f32_e32 v19, 0x42a00000, v19
	v_mul_f32_e32 v19, 0x3fb8aa3b, v19
	v_exp_f32_e32 v21, v19
	v_mul_f32_e32 v19, 0x3d372713, v16
	v_mul_f32_e32 v19, v16, v19
	v_fma_f32 v19, v16, v19, v16
	v_mul_f32_e32 v19, 0xbfcc422a, v19
	v_min_f32_e32 v19, 0x42a00000, v19
	v_mul_f32_e32 v19, 0x3fb8aa3b, v19
	v_exp_f32_e32 v28, v19
	v_mul_f32_e32 v19, 0x3d372713, v17
	v_mul_f32_e32 v19, v17, v19
	v_fma_f32 v19, v17, v19, v17
	v_mul_f32_e32 v19, 0xbfcc422a, v19
	v_pk_add_f32 v[20:21], v[20:21], 1.0 op_sel_hi:[1,0]
	v_min_f32_e32 v19, 0x42a00000, v19
	v_rcp_f32_e32 v26, v20
	v_rcp_f32_e32 v27, v21
	v_mul_f32_e32 v19, 0x3fb8aa3b, v19
	v_exp_f32_e32 v29, v19
	v_or_b32_e32 v18, 48, v124
	v_pk_fma_f32 v[20:21], v[20:21], v[26:27], 1.0 op_sel_hi:[1,1,0] neg_lo:[1,0,0] neg_hi:[1,0,0]
	s_andn2_b64 vcc, exec, s[16:17]
	v_pk_fma_f32 v[20:21], v[26:27], v[20:21], v[26:27]
	v_pk_add_f32 v[26:27], v[28:29], 1.0 op_sel_hi:[1,0]
	v_pk_mul_f32 v[14:15], v[14:15], v[20:21]
	v_rcp_f32_e32 v28, v26
	v_rcp_f32_e32 v29, v27
	v_pk_mul_f32 v[10:11], v[10:11], v[14:15]
	v_pk_fma_f32 v[20:21], v[40:41], v[24:25], v[52:53]
	v_cvt_pk_bf16_f32 v10, v10, v11
	v_pk_fma_f32 v[14:15], v[26:27], v[28:29], 1.0 op_sel_hi:[1,1,0] neg_lo:[1,0,0] neg_hi:[1,0,0]
	v_pk_fma_f32 v[20:21], v[44:45], v[36:37], v[20:21]
	v_pk_fma_f32 v[14:15], v[28:29], v[14:15], v[28:29]
	v_pk_fma_f32 v[8:9], v[8:9], v[48:49], v[20:21]
	v_pk_mul_f32 v[14:15], v[16:17], v[14:15]
	v_pk_fma_f32 v[16:17], v[38:39], v[22:23], v[50:51]
	v_pk_mul_f32 v[12:13], v[12:13], v[14:15]
	v_pk_fma_f32 v[16:17], v[42:43], v[34:35], v[16:17]
	s_mov_b64 s[16:17], -1
	v_pk_fma_f32 v[6:7], v[6:7], v[46:47], v[16:17]
	s_nop 0
	v_mul_f32_e32 v11, 0x3d372713, v6
	v_mul_f32_e32 v11, v6, v11
	v_fma_f32 v11, v6, v11, v6
	v_mul_f32_e32 v11, 0xbfcc422a, v11
	v_min_f32_e32 v11, 0x42a00000, v11
	v_mul_f32_e32 v11, 0x3fb8aa3b, v11
	v_exp_f32_e32 v16, v11
	v_mul_f32_e32 v11, 0x3d372713, v7
	v_mul_f32_e32 v11, v7, v11
	v_fma_f32 v11, v7, v11, v7
	v_mul_f32_e32 v11, 0xbfcc422a, v11
	v_min_f32_e32 v11, 0x42a00000, v11
	v_mul_f32_e32 v11, 0x3fb8aa3b, v11
	v_exp_f32_e32 v17, v11
	v_mul_f32_e32 v11, 0x3d372713, v8
	v_mul_f32_e32 v11, v8, v11
	v_fma_f32 v11, v8, v11, v8
	v_mul_f32_e32 v11, 0xbfcc422a, v11
	v_min_f32_e32 v11, 0x42a00000, v11
	v_mul_f32_e32 v11, 0x3fb8aa3b, v11
	v_exp_f32_e32 v22, v11
	v_mul_f32_e32 v11, 0x3d372713, v9
	v_mul_f32_e32 v11, v9, v11
	v_fma_f32 v11, v9, v11, v9
	v_mul_f32_e32 v11, 0xbfcc422a, v11
	v_min_f32_e32 v11, 0x42a00000, v11
	v_mul_f32_e32 v11, 0x3fb8aa3b, v11
	v_pk_add_f32 v[16:17], v[16:17], 1.0 op_sel_hi:[1,0]
	v_exp_f32_e32 v23, v11
	v_rcp_f32_e32 v20, v16
	v_rcp_f32_e32 v21, v17
	v_cvt_pk_bf16_f32 v11, v12, v13
	v_pk_add_f32 v[14:15], v[22:23], 1.0 op_sel_hi:[1,0]
	v_pk_fma_f32 v[12:13], v[16:17], v[20:21], 1.0 op_sel_hi:[1,1,0] neg_lo:[1,0,0] neg_hi:[1,0,0]
	v_rcp_f32_e32 v16, v14
	v_rcp_f32_e32 v17, v15
	v_pk_fma_f32 v[12:13], v[20:21], v[12:13], v[20:21]
	s_nop 0
	v_pk_mul_f32 v[6:7], v[6:7], v[12:13]
	s_nop 0
	v_pk_mul_f32 v[2:3], v[2:3], v[6:7]
	v_pk_fma_f32 v[6:7], v[14:15], v[16:17], 1.0 op_sel_hi:[1,1,0] neg_lo:[1,0,0] neg_hi:[1,0,0]
	v_cvt_pk_bf16_f32 v12, v2, v3
	v_pk_fma_f32 v[6:7], v[16:17], v[6:7], v[16:17]
	v_mad_i64_i32 v[2:3], s[18:19], v18, s79, v[178:179]
	v_pk_mul_f32 v[6:7], v[8:9], v[6:7]
	s_nop 0
	v_pk_mul_f32 v[4:5], v[4:5], v[6:7]
	s_nop 0
	v_cvt_pk_bf16_f32 v13, v4, v5
	global_store_dwordx4 v[2:3], v[10:13], off sc1
	s_cbranch_vccnz .LBB0_962
	s_andn2_b64 vcc, exec, s[24:25]
	s_cbranch_vccnz .LBB0_961
	s_barrier
	s_branch .LBB0_961
